# back-edge rotation (asm guide 7.11): K-loop counter / pointer updates and exit test moved above the loop-closing barrier in the five GEMM loops
# baseline (speedup 1.0000x reference)
; #define PG8_STAGE(bufoff, gbase, voff) do { _Pragma("unroll") for (int _i = 0; _i < 2; ++_i) \
;         __builtin_amdgcn_global_load_lds((const unsigned*)((const char*)(gbase) + (voff)[_i]), (PG8_LAS unsigned*)(lds + (bufoff) + ldsw + _i * 8192), 16, 0, 0); } while (0)
; #define PG8_LDA(dst, b, h) do { _Pragma("unroll") for (int m = 0; m < 4; ++m) _Pragma("unroll") for (int k = 0; k < 2; ++k) dst[m][k] = *(const PG8_LAS bf16x8*)(lds + PG8_SA(b, h) + aoff + m * 2048 + k * 1024); } while (0)
; #define PG8_LDB(dst, b, h) do { _Pragma("unroll") for (int n = 0; n < 2; ++n) _Pragma("unroll") for (int k = 0; k < 2; ++k) dst[n][k] = *(const PG8_LAS bf16x8*)(lds + PG8_SB(b, h) + boff + n * 2048 + k * 1024); } while (0)
; #define PG8_MMA(ai, bj, At, Bt) do { __builtin_amdgcn_s_setprio(1); _Pragma("unroll") for (int m = 0; m < 4; ++m) _Pragma("unroll") for (int n = 0; n < 2; ++n) _Pragma("unroll") for (int k = 0; k < 2; ++k) \
;         acc[ai][bj][m][n] = __builtin_amdgcn_mfma_f32_16x16x32_bf16(Bt[n][k], At[m][k], acc[ai][bj][m][n], 0, 0, 0); __builtin_amdgcn_s_setprio(0); } while (0)
; #define PG8_WAIT_V(n) asm volatile("s_waitcnt vmcnt(" #n ")" ::: "memory")
; #define PG8_WAIT_L(n) asm volatile("s_waitcnt lgkmcnt(" #n ")" ::: "memory")
; #define PG8_BAR __builtin_amdgcn_s_barrier()
; #define PG8_SCHED __builtin_amdgcn_sched_barrier(0)
; template <class Epi, class Sched, bool ALIGN_EPI = false, bool SP2 = false>
; __device__ __forceinline__ void gemm_phase(PG8_LAS unsigned char* lds, const Gemm g, const Sched& S, const Epi& E) {
;     ...
;             PG8_LDB(B0, 0, 0); PG8_LDB(B1, 0, 1); PG8_SCHED; PG8_LDA(At, 0, 0); PG8_STAGE(PG8_SA(1, 1), a1 + hstepA, voffA);
;             PG8_WAIT_V(8); PG8_WAIT_L(0); PG8_BAR; PG8_MMA(0, 0, At, B0); PG8_MMA(0, 1, At, B1); PG8_BAR; PG8_SCHED;
;             PG8_LDA(At, 0, 1); PG8_STAGE(PG8_SB(0, 0), b2, voffB); PG8_STAGE(PG8_SB(0, 1), b2 + hstepB, voffB); PG8_STAGE(PG8_SA(0, 0), a2, voffA);
;             PG8_WAIT_V(8); PG8_WAIT_L(0); PG8_BAR; PG8_MMA(1, 0, At, B0); PG8_MMA(1, 1, At, B1); PG8_BAR; PG8_SCHED;
.LBB0_157:
	v_add_u32_e32 v136, s2, v139
	ds_read_b128 v[186:189], v136
	ds_read_b128 v[190:193], v136 offset:1024
	ds_read_b128 v[194:197], v136 offset:2048
	ds_read_b128 v[198:201], v136 offset:3072
	v_add_u32_e32 v136, s3, v139
	ds_read_b128 v[202:205], v136
	ds_read_b128 v[206:209], v136 offset:1024
	ds_read_b128 v[210:213], v136 offset:2048
	ds_read_b128 v[214:217], v136 offset:3072
	s_add_u32 s38, s36, 0xfffc0080
	s_addc_u32 s39, s37, -1
	s_cmp_eq_u32 s45, 12
	s_cselect_b32 s41, s7, s39
	s_cselect_b32 s40, s29, s38
	s_cselect_b32 s39, s27, s44
	s_cselect_b32 s38, s42, s43
	v_lshl_add_u64 v[250:251], s[36:37], 0, v[178:179]
	s_add_i32 m0, s63, 0xc000
	ds_read_b128 v[218:221], v159
	ds_read_b128 v[222:225], v159 offset:1024
	ds_read_b128 v[226:229], v159 offset:2048
	ds_read_b128 v[230:233], v159 offset:3072
	ds_read_b128 v[234:237], v159 offset:4096
	ds_read_b128 v[238:241], v159 offset:5120
	ds_read_b128 v[242:245], v159 offset:6144
	ds_read_b128 v[246:249], v159 offset:7168
	global_load_lds_dwordx4 v[250:251], off
	v_lshl_add_u64 v[250:251], s[36:37], 0, v[180:181]
	s_add_i32 m0, s63, 0xe000
	s_nop 0
	global_load_lds_dwordx4 v[250:251], off
	s_waitcnt vmcnt(8)
	s_waitcnt lgkmcnt(0)
	s_barrier
	s_setprio 1
	s_waitcnt lgkmcnt(0)
	v_mfma_f32_16x16x32_bf16 v[124:127], v[186:189], v[218:221], v[124:127]
	v_mfma_f32_16x16x32_bf16 v[120:123], v[194:197], v[218:221], v[120:123]
	v_mfma_f32_16x16x32_bf16 v[108:111], v[186:189], v[226:229], v[108:111]
	v_mfma_f32_16x16x32_bf16 v[104:107], v[194:197], v[226:229], v[104:107]
	v_mfma_f32_16x16x32_bf16 v[92:95], v[186:189], v[234:237], v[92:95]
	v_mfma_f32_16x16x32_bf16 v[88:91], v[194:197], v[234:237], v[88:91]
	v_mfma_f32_16x16x32_bf16 v[76:79], v[186:189], v[242:245], v[76:79]
	v_mfma_f32_16x16x32_bf16 v[72:75], v[194:197], v[242:245], v[72:75]
	v_mfma_f32_16x16x32_bf16 v[124:127], v[190:193], v[222:225], v[124:127]
	v_mfma_f32_16x16x32_bf16 v[120:123], v[198:201], v[222:225], v[120:123]
	v_mfma_f32_16x16x32_bf16 v[108:111], v[190:193], v[230:233], v[108:111]
	v_mfma_f32_16x16x32_bf16 v[104:107], v[198:201], v[230:233], v[104:107]
	v_mfma_f32_16x16x32_bf16 v[92:95], v[190:193], v[238:241], v[92:95]
	v_mfma_f32_16x16x32_bf16 v[88:91], v[198:201], v[238:241], v[88:91]
	v_mfma_f32_16x16x32_bf16 v[76:79], v[190:193], v[246:249], v[76:79]
	v_mfma_f32_16x16x32_bf16 v[72:75], v[198:201], v[246:249], v[72:75]
	s_setprio 0
	s_setprio 1
	v_mfma_f32_16x16x32_bf16 v[116:119], v[202:205], v[218:221], v[116:119]
	v_mfma_f32_16x16x32_bf16 v[112:115], v[210:213], v[218:221], v[112:115]
	v_mfma_f32_16x16x32_bf16 v[100:103], v[202:205], v[226:229], v[100:103]
	v_mfma_f32_16x16x32_bf16 v[96:99], v[210:213], v[226:229], v[96:99]
	v_mfma_f32_16x16x32_bf16 v[84:87], v[202:205], v[234:237], v[84:87]
	v_mfma_f32_16x16x32_bf16 v[80:83], v[210:213], v[234:237], v[80:83]
	v_mfma_f32_16x16x32_bf16 v[68:71], v[202:205], v[242:245], v[68:71]
	v_mfma_f32_16x16x32_bf16 v[64:67], v[210:213], v[242:245], v[64:67]
	v_mfma_f32_16x16x32_bf16 v[116:119], v[206:209], v[222:225], v[116:119]
	v_mfma_f32_16x16x32_bf16 v[112:115], v[214:217], v[222:225], v[112:115]
	v_mfma_f32_16x16x32_bf16 v[100:103], v[206:209], v[230:233], v[100:103]
	v_mfma_f32_16x16x32_bf16 v[96:99], v[214:217], v[230:233], v[96:99]
	v_mfma_f32_16x16x32_bf16 v[84:87], v[206:209], v[238:241], v[84:87]
	v_mfma_f32_16x16x32_bf16 v[80:83], v[214:217], v[238:241], v[80:83]
	v_mfma_f32_16x16x32_bf16 v[68:71], v[206:209], v[246:249], v[68:71]
	v_mfma_f32_16x16x32_bf16 v[64:67], v[214:217], v[246:249], v[64:67]
	s_setprio 0
	s_barrier
	s_add_i32 s46, s2, s62
	v_lshl_add_u64 v[250:251], s[38:39], 0, v[130:131]
	s_mov_b32 m0, s46
	ds_read_b128 v[218:221], v159 offset:16384
	ds_read_b128 v[222:225], v159 offset:17408
	ds_read_b128 v[226:229], v159 offset:18432
	ds_read_b128 v[230:233], v159 offset:19456
	ds_read_b128 v[234:237], v159 offset:20480
	ds_read_b128 v[238:241], v159 offset:21504
	ds_read_b128 v[242:245], v159 offset:22528
	ds_read_b128 v[246:249], v159 offset:23552
	global_load_lds_dwordx4 v[250:251], off
	s_add_i32 m0, s46, 0x2000
	s_add_u32 s46, s38, 0x40000
	v_lshl_add_u64 v[252:253], s[38:39], 0, v[134:135]
	s_addc_u32 s47, s39, 0
	s_add_i32 s48, s3, s62
	global_load_lds_dwordx4 v[252:253], off
	v_lshl_add_u64 v[166:167], s[46:47], 0, v[130:131]
	s_mov_b32 m0, s48
	v_lshl_add_u64 v[168:169], s[40:41], 0, v[132:133]
	global_load_lds_dwordx4 v[166:167], off
	v_lshl_add_u64 v[166:167], s[46:47], 0, v[134:135]
	s_add_i32 m0, s48, 0x2000
	s_nop 0
	global_load_lds_dwordx4 v[166:167], off
	v_lshl_add_u64 v[166:167], s[40:41], 0, v[128:129]
	s_mov_b32 m0, s63
	s_nop 0
	global_load_lds_dwordx4 v[166:167], off
	s_mov_b32 m0, s64
	s_nop 0
	global_load_lds_dwordx4 v[168:169], off
	s_waitcnt vmcnt(8)
	s_waitcnt lgkmcnt(0)
	s_barrier
; #define PG8_STAGE(bufoff, gbase, voff) do { _Pragma("unroll") for (int _i = 0; _i < 2; ++_i) \
;         __builtin_amdgcn_global_load_lds((const unsigned*)((const char*)(gbase) + (voff)[_i]), (PG8_LAS unsigned*)(lds + (bufoff) + ldsw + _i * 8192), 16, 0, 0); } while (0)
; #define PG8_LDA(dst, b, h) do { _Pragma("unroll") for (int m = 0; m < 4; ++m) _Pragma("unroll") for (int k = 0; k < 2; ++k) dst[m][k] = *(const PG8_LAS bf16x8*)(lds + PG8_SA(b, h) + aoff + m * 2048 + k * 1024); } while (0)
; #define PG8_LDB(dst, b, h) do { _Pragma("unroll") for (int n = 0; n < 2; ++n) _Pragma("unroll") for (int k = 0; k < 2; ++k) dst[n][k] = *(const PG8_LAS bf16x8*)(lds + PG8_SB(b, h) + boff + n * 2048 + k * 1024); } while (0)
; #define PG8_MMA(ai, bj, At, Bt) do { __builtin_amdgcn_s_setprio(1); _Pragma("unroll") for (int m = 0; m < 4; ++m) _Pragma("unroll") for (int n = 0; n < 2; ++n) _Pragma("unroll") for (int k = 0; k < 2; ++k) \
;         acc[ai][bj][m][n] = __builtin_amdgcn_mfma_f32_16x16x32_bf16(Bt[n][k], At[m][k], acc[ai][bj][m][n], 0, 0, 0); __builtin_amdgcn_s_setprio(0); } while (0)
; #define PG8_WAIT_V(n) asm volatile("s_waitcnt vmcnt(" #n ")" ::: "memory")
; #define PG8_WAIT_L(n) asm volatile("s_waitcnt lgkmcnt(" #n ")" ::: "memory")
; #define PG8_BAR __builtin_amdgcn_s_barrier()
; #define PG8_SCHED __builtin_amdgcn_sched_barrier(0)
; template <class Epi, class Sched, bool ALIGN_EPI = false, bool SP2 = false>
; __device__ __forceinline__ void gemm_phase(PG8_LAS unsigned char* lds, const Gemm g, const Sched& S, const Epi& E) {
;     ...
;             PG8_WAIT_V(8); PG8_WAIT_L(0); PG8_BAR; PG8_MMA(1, 0, At, B0); PG8_MMA(1, 1, At, B1); PG8_BAR; PG8_SCHED;
;             PG8_LDB(B0, 1, 0); PG8_LDB(B1, 1, 1); PG8_SCHED; PG8_LDA(At, 1, 0); PG8_STAGE(PG8_SA(0, 1), a2 + hstepA, voffA);
;             PG8_WAIT_V(8); PG8_WAIT_L(0); PG8_BAR; PG8_MMA(0, 0, At, B0); PG8_MMA(0, 1, At, B1); PG8_BAR; PG8_SCHED;
	s_setprio 1
	s_waitcnt lgkmcnt(0)
	v_mfma_f32_16x16x32_bf16 v[60:63], v[186:189], v[218:221], v[60:63]
	v_mfma_f32_16x16x32_bf16 v[56:59], v[194:197], v[218:221], v[56:59]
	v_mfma_f32_16x16x32_bf16 v[44:47], v[186:189], v[226:229], v[44:47]
	v_mfma_f32_16x16x32_bf16 v[40:43], v[194:197], v[226:229], v[40:43]
	v_mfma_f32_16x16x32_bf16 v[28:31], v[186:189], v[234:237], v[28:31]
	v_mfma_f32_16x16x32_bf16 v[24:27], v[194:197], v[234:237], v[24:27]
	v_mfma_f32_16x16x32_bf16 v[12:15], v[186:189], v[242:245], v[12:15]
	v_mfma_f32_16x16x32_bf16 v[8:11], v[194:197], v[242:245], v[8:11]
	v_mfma_f32_16x16x32_bf16 v[60:63], v[190:193], v[222:225], v[60:63]
	v_mfma_f32_16x16x32_bf16 v[56:59], v[198:201], v[222:225], v[56:59]
	v_mfma_f32_16x16x32_bf16 v[44:47], v[190:193], v[230:233], v[44:47]
	v_mfma_f32_16x16x32_bf16 v[40:43], v[198:201], v[230:233], v[40:43]
	v_mfma_f32_16x16x32_bf16 v[28:31], v[190:193], v[238:241], v[28:31]
	v_mfma_f32_16x16x32_bf16 v[24:27], v[198:201], v[238:241], v[24:27]
	v_mfma_f32_16x16x32_bf16 v[12:15], v[190:193], v[246:249], v[12:15]
	v_mfma_f32_16x16x32_bf16 v[8:11], v[198:201], v[246:249], v[8:11]
	s_setprio 0
	s_setprio 1
	v_mfma_f32_16x16x32_bf16 v[52:55], v[202:205], v[218:221], v[52:55]
	v_mfma_f32_16x16x32_bf16 v[48:51], v[210:213], v[218:221], v[48:51]
	v_mfma_f32_16x16x32_bf16 v[36:39], v[202:205], v[226:229], v[36:39]
	v_mfma_f32_16x16x32_bf16 v[32:35], v[210:213], v[226:229], v[32:35]
	v_mfma_f32_16x16x32_bf16 v[20:23], v[202:205], v[234:237], v[20:23]
	v_mfma_f32_16x16x32_bf16 v[16:19], v[210:213], v[234:237], v[16:19]
	v_mfma_f32_16x16x32_bf16 v[4:7], v[202:205], v[242:245], v[4:7]
	v_mfma_f32_16x16x32_bf16 v[0:3], v[210:213], v[242:245], v[0:3]
	v_mfma_f32_16x16x32_bf16 v[52:55], v[206:209], v[222:225], v[52:55]
	v_mfma_f32_16x16x32_bf16 v[48:51], v[214:217], v[222:225], v[48:51]
	v_mfma_f32_16x16x32_bf16 v[36:39], v[206:209], v[230:233], v[36:39]
	v_mfma_f32_16x16x32_bf16 v[32:35], v[214:217], v[230:233], v[32:35]
	v_mfma_f32_16x16x32_bf16 v[20:23], v[206:209], v[238:241], v[20:23]
	v_mfma_f32_16x16x32_bf16 v[16:19], v[214:217], v[238:241], v[16:19]
	v_mfma_f32_16x16x32_bf16 v[4:7], v[206:209], v[246:249], v[4:7]
	v_mfma_f32_16x16x32_bf16 v[0:3], v[214:217], v[246:249], v[0:3]
	s_setprio 0
	s_barrier
	s_add_i32 s46, 0, 0x18000
	v_add_u32_e32 v136, s46, v139
	s_add_i32 s47, 0, 0x1c000
	ds_read_b128 v[186:189], v136
	ds_read_b128 v[190:193], v136 offset:1024
	ds_read_b128 v[194:197], v136 offset:2048
	ds_read_b128 v[198:201], v136 offset:3072
	v_add_u32_e32 v136, s47, v139
	ds_read_b128 v[202:205], v136
	ds_read_b128 v[206:209], v136 offset:1024
	ds_read_b128 v[210:213], v136 offset:2048
	ds_read_b128 v[214:217], v136 offset:3072
	s_add_u32 s40, s40, 0x40000
	s_addc_u32 s41, s41, 0
	s_mov_b32 m0, s65
	v_lshl_add_u64 v[170:171], s[40:41], 0, v[128:129]
	ds_read_b128 v[218:221], v159 offset:32768
	ds_read_b128 v[222:225], v159 offset:33792
	ds_read_b128 v[226:229], v159 offset:34816
	ds_read_b128 v[230:233], v159 offset:35840
	ds_read_b128 v[234:237], v159 offset:36864
	ds_read_b128 v[238:241], v159 offset:37888
	ds_read_b128 v[242:245], v159 offset:38912
	ds_read_b128 v[246:249], v159 offset:39936
	global_load_lds_dwordx4 v[170:171], off
	v_lshl_add_u64 v[170:171], s[40:41], 0, v[132:133]
	s_mov_b32 m0, s66
	s_nop 0
	global_load_lds_dwordx4 v[170:171], off
	s_waitcnt vmcnt(8)
	s_waitcnt lgkmcnt(0)
	s_barrier
	s_setprio 1
	s_waitcnt lgkmcnt(0)
	v_mfma_f32_16x16x32_bf16 v[124:127], v[186:189], v[218:221], v[124:127]
	v_mfma_f32_16x16x32_bf16 v[120:123], v[194:197], v[218:221], v[120:123]
	v_mfma_f32_16x16x32_bf16 v[108:111], v[186:189], v[226:229], v[108:111]
	v_mfma_f32_16x16x32_bf16 v[104:107], v[194:197], v[226:229], v[104:107]
	v_mfma_f32_16x16x32_bf16 v[92:95], v[186:189], v[234:237], v[92:95]
	v_mfma_f32_16x16x32_bf16 v[88:91], v[194:197], v[234:237], v[88:91]
	v_mfma_f32_16x16x32_bf16 v[76:79], v[186:189], v[242:245], v[76:79]
	v_mfma_f32_16x16x32_bf16 v[72:75], v[194:197], v[242:245], v[72:75]
	v_mfma_f32_16x16x32_bf16 v[124:127], v[190:193], v[222:225], v[124:127]
	v_mfma_f32_16x16x32_bf16 v[120:123], v[198:201], v[222:225], v[120:123]
	v_mfma_f32_16x16x32_bf16 v[108:111], v[190:193], v[230:233], v[108:111]
	v_mfma_f32_16x16x32_bf16 v[104:107], v[198:201], v[230:233], v[104:107]
	v_mfma_f32_16x16x32_bf16 v[92:95], v[190:193], v[238:241], v[92:95]
	v_mfma_f32_16x16x32_bf16 v[88:91], v[198:201], v[238:241], v[88:91]
	v_mfma_f32_16x16x32_bf16 v[76:79], v[190:193], v[246:249], v[76:79]
	v_mfma_f32_16x16x32_bf16 v[72:75], v[198:201], v[246:249], v[72:75]
	s_setprio 0
	s_setprio 1
	v_mfma_f32_16x16x32_bf16 v[116:119], v[202:205], v[218:221], v[116:119]
	v_mfma_f32_16x16x32_bf16 v[112:115], v[210:213], v[218:221], v[112:115]
	v_mfma_f32_16x16x32_bf16 v[100:103], v[202:205], v[226:229], v[100:103]
	v_mfma_f32_16x16x32_bf16 v[96:99], v[210:213], v[226:229], v[96:99]
	v_mfma_f32_16x16x32_bf16 v[84:87], v[202:205], v[234:237], v[84:87]
	v_mfma_f32_16x16x32_bf16 v[80:83], v[210:213], v[234:237], v[80:83]
	v_mfma_f32_16x16x32_bf16 v[68:71], v[202:205], v[242:245], v[68:71]
	v_mfma_f32_16x16x32_bf16 v[64:67], v[210:213], v[242:245], v[64:67]
	v_mfma_f32_16x16x32_bf16 v[116:119], v[206:209], v[222:225], v[116:119]
	v_mfma_f32_16x16x32_bf16 v[112:115], v[214:217], v[222:225], v[112:115]
	v_mfma_f32_16x16x32_bf16 v[100:103], v[206:209], v[230:233], v[100:103]
	v_mfma_f32_16x16x32_bf16 v[96:99], v[214:217], v[230:233], v[96:99]
	v_mfma_f32_16x16x32_bf16 v[84:87], v[206:209], v[238:241], v[84:87]
	v_mfma_f32_16x16x32_bf16 v[80:83], v[214:217], v[238:241], v[80:83]
	v_mfma_f32_16x16x32_bf16 v[68:71], v[206:209], v[246:249], v[68:71]
	v_mfma_f32_16x16x32_bf16 v[64:67], v[214:217], v[246:249], v[64:67]
	s_setprio 0
	s_barrier
; #define PG8_STAGE(bufoff, gbase, voff) do { _Pragma("unroll") for (int _i = 0; _i < 2; ++_i) \
;         __builtin_amdgcn_global_load_lds((const unsigned*)((const char*)(gbase) + (voff)[_i]), (PG8_LAS unsigned*)(lds + (bufoff) + ldsw + _i * 8192), 16, 0, 0); } while (0)
; #define PG8_LDA(dst, b, h) do { _Pragma("unroll") for (int m = 0; m < 4; ++m) _Pragma("unroll") for (int k = 0; k < 2; ++k) dst[m][k] = *(const PG8_LAS bf16x8*)(lds + PG8_SA(b, h) + aoff + m * 2048 + k * 1024); } while (0)
; #define PG8_MMA(ai, bj, At, Bt) do { __builtin_amdgcn_s_setprio(1); _Pragma("unroll") for (int m = 0; m < 4; ++m) _Pragma("unroll") for (int n = 0; n < 2; ++n) _Pragma("unroll") for (int k = 0; k < 2; ++k) \
;         acc[ai][bj][m][n] = __builtin_amdgcn_mfma_f32_16x16x32_bf16(Bt[n][k], At[m][k], acc[ai][bj][m][n], 0, 0, 0); __builtin_amdgcn_s_setprio(0); } while (0)
; #define PG8_WAIT_V(n) asm volatile("s_waitcnt vmcnt(" #n ")" ::: "memory")
; #define PG8_WAIT_L(n) asm volatile("s_waitcnt lgkmcnt(" #n ")" ::: "memory")
; #define PG8_BAR __builtin_amdgcn_s_barrier()
; #define PG8_SCHED __builtin_amdgcn_sched_barrier(0)
; template <class Epi, class Sched, bool ALIGN_EPI = false, bool SP2 = false>
; __device__ __forceinline__ void gemm_phase(PG8_LAS unsigned char* lds, const Gemm g, const Sched& S, const Epi& E) {
;     ...
;         for (int t = 0; t < nt; t += 2) {
;     ...
;             PG8_LDA(At, 1, 1); PG8_STAGE(PG8_SB(1, 0), b3, voffB); PG8_STAGE(PG8_SB(1, 1), b3 + hstepB, voffB); PG8_STAGE(PG8_SA(1, 0), a3, voffA);
;             PG8_WAIT_V(8); PG8_WAIT_L(0); PG8_BAR; PG8_MMA(1, 0, At, B0); PG8_MMA(1, 1, At, B1); PG8_BAR; PG8_SCHED;
	s_add_i32 s40, s46, s62
	v_lshl_add_u64 v[170:171], v[250:251], 0, s[22:23]
	s_mov_b32 m0, s40
	ds_read_b128 v[218:221], v159 offset:49152
	ds_read_b128 v[222:225], v159 offset:50176
	ds_read_b128 v[226:229], v159 offset:51200
	ds_read_b128 v[230:233], v159 offset:52224
	ds_read_b128 v[234:237], v159 offset:53248
	ds_read_b128 v[238:241], v159 offset:54272
	ds_read_b128 v[242:245], v159 offset:55296
	ds_read_b128 v[246:249], v159 offset:56320
	global_load_lds_dwordx4 v[170:171], off
	s_add_i32 m0, s40, 0x2000
	s_add_u32 s38, s38, 0x40080
	v_lshl_add_u64 v[170:171], v[252:253], 0, s[22:23]
	s_addc_u32 s39, s39, 0
	s_add_i32 s40, s47, s62
	global_load_lds_dwordx4 v[170:171], off
	v_lshl_add_u64 v[170:171], s[38:39], 0, v[130:131]
	s_mov_b32 m0, s40
	v_lshl_add_u64 v[166:167], v[166:167], 0, s[22:23]
	global_load_lds_dwordx4 v[170:171], off
	v_lshl_add_u64 v[170:171], s[38:39], 0, v[134:135]
	s_add_i32 m0, s40, 0x2000
	s_nop 0
	global_load_lds_dwordx4 v[170:171], off
	s_mov_b32 m0, s93
	s_nop 0
	global_load_lds_dwordx4 v[166:167], off
	v_lshl_add_u64 v[166:167], v[168:169], 0, s[22:23]
	s_mov_b32 m0, s96
	s_nop 0
	global_load_lds_dwordx4 v[166:167], off
	s_waitcnt vmcnt(8)
	s_waitcnt lgkmcnt(0)
	s_barrier
	s_setprio 1
	s_waitcnt lgkmcnt(0)
	v_mfma_f32_16x16x32_bf16 v[60:63], v[186:189], v[218:221], v[60:63]
	v_mfma_f32_16x16x32_bf16 v[56:59], v[194:197], v[218:221], v[56:59]
	v_mfma_f32_16x16x32_bf16 v[44:47], v[186:189], v[226:229], v[44:47]
	v_mfma_f32_16x16x32_bf16 v[40:43], v[194:197], v[226:229], v[40:43]
	v_mfma_f32_16x16x32_bf16 v[28:31], v[186:189], v[234:237], v[28:31]
	v_mfma_f32_16x16x32_bf16 v[24:27], v[194:197], v[234:237], v[24:27]
	v_mfma_f32_16x16x32_bf16 v[12:15], v[186:189], v[242:245], v[12:15]
	v_mfma_f32_16x16x32_bf16 v[8:11], v[194:197], v[242:245], v[8:11]
	v_mfma_f32_16x16x32_bf16 v[60:63], v[190:193], v[222:225], v[60:63]
	v_mfma_f32_16x16x32_bf16 v[56:59], v[198:201], v[222:225], v[56:59]
	v_mfma_f32_16x16x32_bf16 v[44:47], v[190:193], v[230:233], v[44:47]
	v_mfma_f32_16x16x32_bf16 v[40:43], v[198:201], v[230:233], v[40:43]
	v_mfma_f32_16x16x32_bf16 v[28:31], v[190:193], v[238:241], v[28:31]
	v_mfma_f32_16x16x32_bf16 v[24:27], v[198:201], v[238:241], v[24:27]
	v_mfma_f32_16x16x32_bf16 v[12:15], v[190:193], v[246:249], v[12:15]
	v_mfma_f32_16x16x32_bf16 v[8:11], v[198:201], v[246:249], v[8:11]
	s_setprio 0
	s_setprio 1
	v_mfma_f32_16x16x32_bf16 v[52:55], v[202:205], v[218:221], v[52:55]
	v_mfma_f32_16x16x32_bf16 v[48:51], v[210:213], v[218:221], v[48:51]
	v_mfma_f32_16x16x32_bf16 v[36:39], v[202:205], v[226:229], v[36:39]
	v_mfma_f32_16x16x32_bf16 v[32:35], v[210:213], v[226:229], v[32:35]
	v_mfma_f32_16x16x32_bf16 v[20:23], v[202:205], v[234:237], v[20:23]
	v_mfma_f32_16x16x32_bf16 v[16:19], v[210:213], v[234:237], v[16:19]
	v_mfma_f32_16x16x32_bf16 v[4:7], v[202:205], v[242:245], v[4:7]
	v_mfma_f32_16x16x32_bf16 v[0:3], v[210:213], v[242:245], v[0:3]
	v_mfma_f32_16x16x32_bf16 v[52:55], v[206:209], v[222:225], v[52:55]
	v_mfma_f32_16x16x32_bf16 v[48:51], v[214:217], v[222:225], v[48:51]
	v_mfma_f32_16x16x32_bf16 v[36:39], v[206:209], v[230:233], v[36:39]
	v_mfma_f32_16x16x32_bf16 v[32:35], v[214:217], v[230:233], v[32:35]
	v_mfma_f32_16x16x32_bf16 v[20:23], v[206:209], v[238:241], v[20:23]
	v_mfma_f32_16x16x32_bf16 v[16:19], v[214:217], v[238:241], v[16:19]
	v_mfma_f32_16x16x32_bf16 v[4:7], v[206:209], v[246:249], v[4:7]
	v_mfma_f32_16x16x32_bf16 v[0:3], v[214:217], v[246:249], v[0:3]
	s_add_i32 s45, s45, 2
	s_add_u32 s36, s36, 0x100
	s_addc_u32 s37, s37, 0
	s_add_u32 s43, s43, 0x100
	s_addc_u32 s44, s44, 0
	s_cmp_gt_u32 s45, 13
	s_setprio 0
	s_barrier
	s_cbranch_scc0 .LBB0_157
	s_and_b64 vcc, exec, s[24:25]
	s_cbranch_vccz .LBB0_160
	s_barrier

; #define PG8_STAGE(bufoff, gbase, voff) do { _Pragma("unroll") for (int _i = 0; _i < 2; ++_i) \
;         __builtin_amdgcn_global_load_lds((const unsigned*)((const char*)(gbase) + (voff)[_i]), (PG8_LAS unsigned*)(lds + (bufoff) + ldsw + _i * 8192), 16, 0, 0); } while (0)
; #define PG8_LDA(dst, b, h) do { _Pragma("unroll") for (int m = 0; m < 4; ++m) _Pragma("unroll") for (int k = 0; k < 2; ++k) dst[m][k] = *(const PG8_LAS bf16x8*)(lds + PG8_SA(b, h) + aoff + m * 2048 + k * 1024); } while (0)
; #define PG8_LDB(dst, b, h) do { _Pragma("unroll") for (int n = 0; n < 2; ++n) _Pragma("unroll") for (int k = 0; k < 2; ++k) dst[n][k] = *(const PG8_LAS bf16x8*)(lds + PG8_SB(b, h) + boff + n * 2048 + k * 1024); } while (0)
; #define PG8_MMA(ai, bj, At, Bt) do { __builtin_amdgcn_s_setprio(1); _Pragma("unroll") for (int m = 0; m < 4; ++m) _Pragma("unroll") for (int n = 0; n < 2; ++n) _Pragma("unroll") for (int k = 0; k < 2; ++k) \
;         acc[ai][bj][m][n] = __builtin_amdgcn_mfma_f32_16x16x32_bf16(Bt[n][k], At[m][k], acc[ai][bj][m][n], 0, 0, 0); __builtin_amdgcn_s_setprio(0); } while (0)
; #define PG8_WAIT_V(n) asm volatile("s_waitcnt vmcnt(" #n ")" ::: "memory")
; #define PG8_WAIT_L(n) asm volatile("s_waitcnt lgkmcnt(" #n ")" ::: "memory")
; #define PG8_BAR __builtin_amdgcn_s_barrier()
; template <class Epi, class Sched, bool ALIGN_EPI = false, bool SP2 = false>
; __device__ __forceinline__ void gemm_phase(PG8_LAS unsigned char* lds, const Gemm g, const Sched& S, const Epi& E) {
;     ...
;             const char* a1 = cA + (size_t)(t + 1) * kstep;
;             const char* a2 = last ? nA : cA + (size_t)(t + 2) * kstep; const char* b2 = last ? nB : cB + (size_t)(t + 2) * kstep;
;             const char* a3 = a2 + kstep; const char* b3 = b2 + kstep;
;             if (last && has_next) S.a_ready(nxt);
;             if constexpr (SP2) {
;             PG8_LDB(B0, 0, 0); PG8_LDB(B1, 0, 1); PG8_SCHED; PG8_LDA(At, 0, 0); PG8_STAGE(PG8_SA(1, 1), a1 + hstepA, voffA);
;             PG8_WAIT_V(8); PG8_WAIT_L(0); PG8_BAR; PG8_MMA(0, 0, At, B0); PG8_MMA(0, 1, At, B1); PG8_BAR; PG8_SCHED;
;             PG8_LDA(At, 0, 1); PG8_STAGE(PG8_SB(0, 0), b2, voffB); PG8_STAGE(PG8_SB(0, 1), b2 + hstepB, voffB); PG8_STAGE(PG8_SA(0, 0), a2, voffA);
;             PG8_WAIT_V(8); PG8_WAIT_L(0); PG8_BAR; PG8_MMA(1, 0, At, B0); PG8_MMA(1, 1, At, B1); PG8_BAR; PG8_SCHED;
.LBB0_470:
	ds_read_b128 v[158:161], v155
	ds_read_b128 v[162:165], v155 offset:1024
	ds_read_b128 v[166:169], v155 offset:2048
	ds_read_b128 v[170:173], v155 offset:3072
	ds_read_b128 v[174:177], v156
	ds_read_b128 v[178:181], v156 offset:1024
	ds_read_b128 v[186:189], v156 offset:2048
	ds_read_b128 v[190:193], v156 offset:3072
	s_add_u32 s12, s0, 0xfffc0080
	s_addc_u32 s13, s1, -1
	s_cmp_eq_u32 s44, 4
	s_cselect_b32 s17, s38, s13
	s_cselect_b32 s16, s39, s12
	s_cselect_b32 s13, s40, s43
	s_cselect_b32 s12, s41, s42
	v_lshl_add_u64 v[182:183], s[0:1], 0, v[140:141]
	s_add_i32 m0, s22, 0xc000
	ds_read_b128 v[194:197], v157
	ds_read_b128 v[198:201], v157 offset:1024
	ds_read_b128 v[202:205], v157 offset:2048
	ds_read_b128 v[206:209], v157 offset:3072
	ds_read_b128 v[210:213], v157 offset:4096
	ds_read_b128 v[214:217], v157 offset:5120
	ds_read_b128 v[218:221], v157 offset:6144
	ds_read_b128 v[222:225], v157 offset:7168
	global_load_lds_dwordx4 v[182:183], off
	v_lshl_add_u64 v[182:183], s[0:1], 0, v[142:143]
	s_add_i32 m0, s22, 0xe000
	s_nop 0
	global_load_lds_dwordx4 v[182:183], off
	s_waitcnt vmcnt(8)
	s_waitcnt lgkmcnt(0)
	s_barrier
	s_setprio 1
	s_waitcnt lgkmcnt(0)
	v_mfma_f32_16x16x32_bf16 v[124:127], v[158:161], v[194:197], v[124:127]
	v_mfma_f32_16x16x32_bf16 v[120:123], v[166:169], v[194:197], v[120:123]
	v_mfma_f32_16x16x32_bf16 v[116:119], v[158:161], v[202:205], v[116:119]
	v_mfma_f32_16x16x32_bf16 v[112:115], v[166:169], v[202:205], v[112:115]
	v_mfma_f32_16x16x32_bf16 v[108:111], v[158:161], v[210:213], v[108:111]
	v_mfma_f32_16x16x32_bf16 v[100:103], v[166:169], v[210:213], v[100:103]
	v_mfma_f32_16x16x32_bf16 v[92:95], v[158:161], v[218:221], v[92:95]
	v_mfma_f32_16x16x32_bf16 v[84:87], v[166:169], v[218:221], v[84:87]
	v_mfma_f32_16x16x32_bf16 v[124:127], v[162:165], v[198:201], v[124:127]
	v_mfma_f32_16x16x32_bf16 v[120:123], v[170:173], v[198:201], v[120:123]
	v_mfma_f32_16x16x32_bf16 v[116:119], v[162:165], v[206:209], v[116:119]
	v_mfma_f32_16x16x32_bf16 v[112:115], v[170:173], v[206:209], v[112:115]
	v_mfma_f32_16x16x32_bf16 v[108:111], v[162:165], v[214:217], v[108:111]
	v_mfma_f32_16x16x32_bf16 v[100:103], v[170:173], v[214:217], v[100:103]
	v_mfma_f32_16x16x32_bf16 v[92:95], v[162:165], v[222:225], v[92:95]
	v_mfma_f32_16x16x32_bf16 v[84:87], v[170:173], v[222:225], v[84:87]
	s_setprio 0
	s_setprio 1
	v_mfma_f32_16x16x32_bf16 v[104:107], v[174:177], v[194:197], v[104:107]
	v_mfma_f32_16x16x32_bf16 v[96:99], v[186:189], v[194:197], v[96:99]
	v_mfma_f32_16x16x32_bf16 v[88:91], v[174:177], v[202:205], v[88:91]
	v_mfma_f32_16x16x32_bf16 v[80:83], v[186:189], v[202:205], v[80:83]
	v_mfma_f32_16x16x32_bf16 v[76:79], v[174:177], v[210:213], v[76:79]
	v_mfma_f32_16x16x32_bf16 v[72:75], v[186:189], v[210:213], v[72:75]
	v_mfma_f32_16x16x32_bf16 v[68:71], v[174:177], v[218:221], v[68:71]
	v_mfma_f32_16x16x32_bf16 v[64:67], v[186:189], v[218:221], v[64:67]
	v_mfma_f32_16x16x32_bf16 v[104:107], v[178:181], v[198:201], v[104:107]
	v_mfma_f32_16x16x32_bf16 v[96:99], v[190:193], v[198:201], v[96:99]
	v_mfma_f32_16x16x32_bf16 v[88:91], v[178:181], v[206:209], v[88:91]
	v_mfma_f32_16x16x32_bf16 v[80:83], v[190:193], v[206:209], v[80:83]
	v_mfma_f32_16x16x32_bf16 v[76:79], v[178:181], v[214:217], v[76:79]
	v_mfma_f32_16x16x32_bf16 v[72:75], v[190:193], v[214:217], v[72:75]
	v_mfma_f32_16x16x32_bf16 v[68:71], v[178:181], v[222:225], v[68:71]
	v_mfma_f32_16x16x32_bf16 v[64:67], v[190:193], v[222:225], v[64:67]
	s_setprio 0
	s_barrier
	s_add_i32 s45, s33, s15
	v_lshl_add_u64 v[182:183], s[12:13], 0, v[132:133]
	s_mov_b32 m0, s45
	ds_read_b128 v[194:197], v157 offset:16384
	ds_read_b128 v[198:201], v157 offset:17408
	ds_read_b128 v[202:205], v157 offset:18432
	ds_read_b128 v[206:209], v157 offset:19456
	ds_read_b128 v[210:213], v157 offset:20480
	ds_read_b128 v[214:217], v157 offset:21504
	ds_read_b128 v[218:221], v157 offset:22528
	ds_read_b128 v[222:225], v157 offset:23552
	global_load_lds_dwordx4 v[182:183], off
	s_add_i32 m0, s45, 0x2000
	s_add_u32 s46, s12, 0x80000
	v_lshl_add_u64 v[226:227], s[12:13], 0, v[128:129]
	s_addc_u32 s47, s13, 0
	s_add_i32 s45, s34, s15
	global_load_lds_dwordx4 v[226:227], off
	v_lshl_add_u64 v[228:229], s[46:47], 0, v[132:133]
	s_mov_b32 m0, s45
	v_lshl_add_u64 v[230:231], s[16:17], 0, v[130:131]
	global_load_lds_dwordx4 v[228:229], off
	v_lshl_add_u64 v[228:229], s[46:47], 0, v[128:129]
	s_add_i32 m0, s45, 0x2000
	s_nop 0
	global_load_lds_dwordx4 v[228:229], off
	v_lshl_add_u64 v[228:229], s[16:17], 0, v[134:135]
	s_mov_b32 m0, s22
	s_nop 0
	global_load_lds_dwordx4 v[228:229], off
	s_mov_b32 m0, s25
	s_nop 0
	global_load_lds_dwordx4 v[230:231], off
	s_waitcnt vmcnt(8)
	s_waitcnt lgkmcnt(0)
	s_barrier
; #define PG8_STAGE(bufoff, gbase, voff) do { _Pragma("unroll") for (int _i = 0; _i < 2; ++_i) \
;         __builtin_amdgcn_global_load_lds((const unsigned*)((const char*)(gbase) + (voff)[_i]), (PG8_LAS unsigned*)(lds + (bufoff) + ldsw + _i * 8192), 16, 0, 0); } while (0)
; #define PG8_LDA(dst, b, h) do { _Pragma("unroll") for (int m = 0; m < 4; ++m) _Pragma("unroll") for (int k = 0; k < 2; ++k) dst[m][k] = *(const PG8_LAS bf16x8*)(lds + PG8_SA(b, h) + aoff + m * 2048 + k * 1024); } while (0)
; #define PG8_LDB(dst, b, h) do { _Pragma("unroll") for (int n = 0; n < 2; ++n) _Pragma("unroll") for (int k = 0; k < 2; ++k) dst[n][k] = *(const PG8_LAS bf16x8*)(lds + PG8_SB(b, h) + boff + n * 2048 + k * 1024); } while (0)
; #define PG8_MMA(ai, bj, At, Bt) do { __builtin_amdgcn_s_setprio(1); _Pragma("unroll") for (int m = 0; m < 4; ++m) _Pragma("unroll") for (int n = 0; n < 2; ++n) _Pragma("unroll") for (int k = 0; k < 2; ++k) \
;         acc[ai][bj][m][n] = __builtin_amdgcn_mfma_f32_16x16x32_bf16(Bt[n][k], At[m][k], acc[ai][bj][m][n], 0, 0, 0); __builtin_amdgcn_s_setprio(0); } while (0)
; #define PG8_WAIT_V(n) asm volatile("s_waitcnt vmcnt(" #n ")" ::: "memory")
; #define PG8_WAIT_L(n) asm volatile("s_waitcnt lgkmcnt(" #n ")" ::: "memory")
; #define PG8_BAR __builtin_amdgcn_s_barrier()
; #define PG8_SCHED __builtin_amdgcn_sched_barrier(0)
; template <class Epi, class Sched, bool ALIGN_EPI = false, bool SP2 = false>
; __device__ __forceinline__ void gemm_phase(PG8_LAS unsigned char* lds, const Gemm g, const Sched& S, const Epi& E) {
;     ...
;             PG8_WAIT_V(8); PG8_WAIT_L(0); PG8_BAR; PG8_MMA(1, 0, At, B0); PG8_MMA(1, 1, At, B1); PG8_BAR; PG8_SCHED;
;             PG8_LDB(B0, 1, 0); PG8_LDB(B1, 1, 1); PG8_SCHED; PG8_LDA(At, 1, 0); PG8_STAGE(PG8_SA(0, 1), a2 + hstepA, voffA);
;             PG8_WAIT_V(8); PG8_WAIT_L(0); PG8_BAR; PG8_MMA(0, 0, At, B0); PG8_MMA(0, 1, At, B1); PG8_BAR; PG8_SCHED;
	s_setprio 1
	s_waitcnt lgkmcnt(0)
	v_mfma_f32_16x16x32_bf16 v[60:63], v[158:161], v[194:197], v[60:63]
	v_mfma_f32_16x16x32_bf16 v[56:59], v[166:169], v[194:197], v[56:59]
	v_mfma_f32_16x16x32_bf16 v[52:55], v[158:161], v[202:205], v[52:55]
	v_mfma_f32_16x16x32_bf16 v[48:51], v[166:169], v[202:205], v[48:51]
	v_mfma_f32_16x16x32_bf16 v[44:47], v[158:161], v[210:213], v[44:47]
	v_mfma_f32_16x16x32_bf16 v[36:39], v[166:169], v[210:213], v[36:39]
	v_mfma_f32_16x16x32_bf16 v[28:31], v[158:161], v[218:221], v[28:31]
	v_mfma_f32_16x16x32_bf16 v[20:23], v[166:169], v[218:221], v[20:23]
	v_mfma_f32_16x16x32_bf16 v[60:63], v[162:165], v[198:201], v[60:63]
	v_mfma_f32_16x16x32_bf16 v[56:59], v[170:173], v[198:201], v[56:59]
	v_mfma_f32_16x16x32_bf16 v[52:55], v[162:165], v[206:209], v[52:55]
	v_mfma_f32_16x16x32_bf16 v[48:51], v[170:173], v[206:209], v[48:51]
	v_mfma_f32_16x16x32_bf16 v[44:47], v[162:165], v[214:217], v[44:47]
	v_mfma_f32_16x16x32_bf16 v[36:39], v[170:173], v[214:217], v[36:39]
	v_mfma_f32_16x16x32_bf16 v[28:31], v[162:165], v[222:225], v[28:31]
	v_mfma_f32_16x16x32_bf16 v[20:23], v[170:173], v[222:225], v[20:23]
	s_setprio 0
	s_setprio 1
	v_mfma_f32_16x16x32_bf16 v[40:43], v[174:177], v[194:197], v[40:43]
	v_mfma_f32_16x16x32_bf16 v[32:35], v[186:189], v[194:197], v[32:35]
	v_mfma_f32_16x16x32_bf16 v[24:27], v[174:177], v[202:205], v[24:27]
	v_mfma_f32_16x16x32_bf16 v[16:19], v[186:189], v[202:205], v[16:19]
	v_mfma_f32_16x16x32_bf16 v[12:15], v[174:177], v[210:213], v[12:15]
	v_mfma_f32_16x16x32_bf16 v[8:11], v[186:189], v[210:213], v[8:11]
	v_mfma_f32_16x16x32_bf16 v[4:7], v[174:177], v[218:221], v[4:7]
	v_mfma_f32_16x16x32_bf16 v[0:3], v[186:189], v[218:221], v[0:3]
	v_mfma_f32_16x16x32_bf16 v[40:43], v[178:181], v[198:201], v[40:43]
	v_mfma_f32_16x16x32_bf16 v[32:35], v[190:193], v[198:201], v[32:35]
	v_mfma_f32_16x16x32_bf16 v[24:27], v[178:181], v[206:209], v[24:27]
	v_mfma_f32_16x16x32_bf16 v[16:19], v[190:193], v[206:209], v[16:19]
	v_mfma_f32_16x16x32_bf16 v[12:15], v[178:181], v[214:217], v[12:15]
	v_mfma_f32_16x16x32_bf16 v[8:11], v[190:193], v[214:217], v[8:11]
	v_mfma_f32_16x16x32_bf16 v[4:7], v[178:181], v[222:225], v[4:7]
	v_mfma_f32_16x16x32_bf16 v[0:3], v[190:193], v[222:225], v[0:3]
	s_setprio 0
	s_barrier
	s_add_i32 s45, 0, 0x18000
	v_add_u32_e32 v136, s45, v150
	s_add_i32 s46, 0, 0x1c000
	ds_read_b128 v[158:161], v136
	ds_read_b128 v[162:165], v136 offset:1024
	ds_read_b128 v[166:169], v136 offset:2048
	ds_read_b128 v[170:173], v136 offset:3072
	v_add_u32_e32 v136, s46, v150
	ds_read_b128 v[174:177], v136
	ds_read_b128 v[178:181], v136 offset:1024
	ds_read_b128 v[186:189], v136 offset:2048
	ds_read_b128 v[190:193], v136 offset:3072
	s_add_u32 s16, s16, 0x40000
	s_addc_u32 s17, s17, 0
	s_mov_b32 m0, s26
	v_lshl_add_u64 v[232:233], s[16:17], 0, v[134:135]
	ds_read_b128 v[194:197], v157 offset:32768
	ds_read_b128 v[198:201], v157 offset:33792
	ds_read_b128 v[202:205], v157 offset:34816
	ds_read_b128 v[206:209], v157 offset:35840
	ds_read_b128 v[210:213], v157 offset:36864
	ds_read_b128 v[214:217], v157 offset:37888
	ds_read_b128 v[218:221], v157 offset:38912
	ds_read_b128 v[222:225], v157 offset:39936
	global_load_lds_dwordx4 v[232:233], off
	v_lshl_add_u64 v[232:233], s[16:17], 0, v[130:131]
	s_mov_b32 m0, s27
	s_nop 0
	global_load_lds_dwordx4 v[232:233], off
	s_waitcnt vmcnt(8)
	s_waitcnt lgkmcnt(0)
	s_barrier
	s_setprio 1
	s_waitcnt lgkmcnt(0)
	v_mfma_f32_16x16x32_bf16 v[124:127], v[158:161], v[194:197], v[124:127]
	v_mfma_f32_16x16x32_bf16 v[120:123], v[166:169], v[194:197], v[120:123]
	v_mfma_f32_16x16x32_bf16 v[116:119], v[158:161], v[202:205], v[116:119]
	v_mfma_f32_16x16x32_bf16 v[112:115], v[166:169], v[202:205], v[112:115]
	v_mfma_f32_16x16x32_bf16 v[108:111], v[158:161], v[210:213], v[108:111]
	v_mfma_f32_16x16x32_bf16 v[100:103], v[166:169], v[210:213], v[100:103]
	v_mfma_f32_16x16x32_bf16 v[92:95], v[158:161], v[218:221], v[92:95]
	v_mfma_f32_16x16x32_bf16 v[84:87], v[166:169], v[218:221], v[84:87]
	v_mfma_f32_16x16x32_bf16 v[124:127], v[162:165], v[198:201], v[124:127]
	v_mfma_f32_16x16x32_bf16 v[120:123], v[170:173], v[198:201], v[120:123]
	v_mfma_f32_16x16x32_bf16 v[116:119], v[162:165], v[206:209], v[116:119]
	v_mfma_f32_16x16x32_bf16 v[112:115], v[170:173], v[206:209], v[112:115]
	v_mfma_f32_16x16x32_bf16 v[108:111], v[162:165], v[214:217], v[108:111]
	v_mfma_f32_16x16x32_bf16 v[100:103], v[170:173], v[214:217], v[100:103]
	v_mfma_f32_16x16x32_bf16 v[92:95], v[162:165], v[222:225], v[92:95]
	v_mfma_f32_16x16x32_bf16 v[84:87], v[170:173], v[222:225], v[84:87]
	s_setprio 0
	s_setprio 1
	v_mfma_f32_16x16x32_bf16 v[104:107], v[174:177], v[194:197], v[104:107]
	v_mfma_f32_16x16x32_bf16 v[96:99], v[186:189], v[194:197], v[96:99]
	v_mfma_f32_16x16x32_bf16 v[88:91], v[174:177], v[202:205], v[88:91]
	v_mfma_f32_16x16x32_bf16 v[80:83], v[186:189], v[202:205], v[80:83]
	v_mfma_f32_16x16x32_bf16 v[76:79], v[174:177], v[210:213], v[76:79]
	v_mfma_f32_16x16x32_bf16 v[72:75], v[186:189], v[210:213], v[72:75]
	v_mfma_f32_16x16x32_bf16 v[68:71], v[174:177], v[218:221], v[68:71]
	v_mfma_f32_16x16x32_bf16 v[64:67], v[186:189], v[218:221], v[64:67]
	v_mfma_f32_16x16x32_bf16 v[104:107], v[178:181], v[198:201], v[104:107]
	v_mfma_f32_16x16x32_bf16 v[96:99], v[190:193], v[198:201], v[96:99]
	v_mfma_f32_16x16x32_bf16 v[88:91], v[178:181], v[206:209], v[88:91]
	v_mfma_f32_16x16x32_bf16 v[80:83], v[190:193], v[206:209], v[80:83]
	v_mfma_f32_16x16x32_bf16 v[76:79], v[178:181], v[214:217], v[76:79]
	v_mfma_f32_16x16x32_bf16 v[72:75], v[190:193], v[214:217], v[72:75]
	v_mfma_f32_16x16x32_bf16 v[68:71], v[178:181], v[222:225], v[68:71]
	v_mfma_f32_16x16x32_bf16 v[64:67], v[190:193], v[222:225], v[64:67]
	s_setprio 0
	s_barrier
; #define PG8_STAGE(bufoff, gbase, voff) do { _Pragma("unroll") for (int _i = 0; _i < 2; ++_i) \
;         __builtin_amdgcn_global_load_lds((const unsigned*)((const char*)(gbase) + (voff)[_i]), (PG8_LAS unsigned*)(lds + (bufoff) + ldsw + _i * 8192), 16, 0, 0); } while (0)
; #define PG8_LDA(dst, b, h) do { _Pragma("unroll") for (int m = 0; m < 4; ++m) _Pragma("unroll") for (int k = 0; k < 2; ++k) dst[m][k] = *(const PG8_LAS bf16x8*)(lds + PG8_SA(b, h) + aoff + m * 2048 + k * 1024); } while (0)
; #define PG8_MMA(ai, bj, At, Bt) do { __builtin_amdgcn_s_setprio(1); _Pragma("unroll") for (int m = 0; m < 4; ++m) _Pragma("unroll") for (int n = 0; n < 2; ++n) _Pragma("unroll") for (int k = 0; k < 2; ++k) \
;         acc[ai][bj][m][n] = __builtin_amdgcn_mfma_f32_16x16x32_bf16(Bt[n][k], At[m][k], acc[ai][bj][m][n], 0, 0, 0); __builtin_amdgcn_s_setprio(0); } while (0)
; #define PG8_WAIT_V(n) asm volatile("s_waitcnt vmcnt(" #n ")" ::: "memory")
; #define PG8_WAIT_L(n) asm volatile("s_waitcnt lgkmcnt(" #n ")" ::: "memory")
; #define PG8_BAR __builtin_amdgcn_s_barrier()
; #define PG8_SCHED __builtin_amdgcn_sched_barrier(0)
; template <class Epi, class Sched, bool ALIGN_EPI = false, bool SP2 = false>
; __device__ __forceinline__ void gemm_phase(PG8_LAS unsigned char* lds, const Gemm g, const Sched& S, const Epi& E) {
;     ...
;         for (int t = 0; t < nt; t += 2) {
;     ...
;             PG8_LDA(At, 1, 1); PG8_STAGE(PG8_SB(1, 0), b3, voffB); PG8_STAGE(PG8_SB(1, 1), b3 + hstepB, voffB); PG8_STAGE(PG8_SA(1, 0), a3, voffA);
;             PG8_WAIT_V(8); PG8_WAIT_L(0); PG8_BAR; PG8_MMA(1, 0, At, B0); PG8_MMA(1, 1, At, B1); PG8_BAR; PG8_SCHED;
;     __device__ __forceinline__ void operator()(const f32x4 (&acc)[2][2][4][2], const pg8::Unit& u, int wr, int wc, int fr, int fq) const {
;         float* base = part + (size_t)(u.koff >> 10) * 8192 * 256;
; #pragma unroll
;         for (int ai = 0; ai < 2; ++ai)
; #pragma unroll
;             for (int m = 0; m < 4; ++m) {
;                 const int row = u.pm * 256 + ai * 128 + wr * 64 + m * 16 + fr;
; #pragma unroll
;                 for (int bj = 0; bj < 2; ++bj) {
;                     float* p = base + (size_t)row * 256 + 128 * bj + 32 * wc + 8 * fq;
;                     *(f32x4*)p = acc[ai][bj][m][0]; *(f32x4*)(p + 4) = acc[ai][bj][m][1];
;                 }
;             }
	s_add_i32 s16, s45, s15
	v_lshl_add_u64 v[182:183], v[182:183], 0, s[10:11]
	s_mov_b32 m0, s16
	ds_read_b128 v[194:197], v157 offset:49152
	ds_read_b128 v[198:201], v157 offset:50176
	ds_read_b128 v[202:205], v157 offset:51200
	ds_read_b128 v[206:209], v157 offset:52224
	ds_read_b128 v[210:213], v157 offset:53248
	ds_read_b128 v[214:217], v157 offset:54272
	ds_read_b128 v[218:221], v157 offset:55296
	ds_read_b128 v[222:225], v157 offset:56320
	global_load_lds_dwordx4 v[182:183], off
	s_add_i32 m0, s16, 0x2000
	s_add_u32 s12, s12, 0x80080
	v_lshl_add_u64 v[182:183], v[226:227], 0, s[10:11]
	s_addc_u32 s13, s13, 0
	s_add_i32 s16, s46, s15
	global_load_lds_dwordx4 v[182:183], off
	v_lshl_add_u64 v[182:183], s[12:13], 0, v[132:133]
	s_mov_b32 m0, s16
	s_nop 0
	global_load_lds_dwordx4 v[182:183], off
	v_lshl_add_u64 v[182:183], s[12:13], 0, v[128:129]
	s_add_i32 m0, s16, 0x2000
	s_nop 0
	global_load_lds_dwordx4 v[182:183], off
	v_lshl_add_u64 v[182:183], v[228:229], 0, s[10:11]
	s_mov_b32 m0, s30
	s_nop 0
	global_load_lds_dwordx4 v[182:183], off
	v_lshl_add_u64 v[182:183], v[230:231], 0, s[10:11]
	s_mov_b32 m0, s31
	s_nop 0
	global_load_lds_dwordx4 v[182:183], off
	s_waitcnt vmcnt(8)
	s_waitcnt lgkmcnt(0)
	s_barrier
	s_setprio 1
	s_waitcnt lgkmcnt(0)
	v_mfma_f32_16x16x32_bf16 v[60:63], v[158:161], v[194:197], v[60:63]
	v_mfma_f32_16x16x32_bf16 v[56:59], v[166:169], v[194:197], v[56:59]
	v_mfma_f32_16x16x32_bf16 v[52:55], v[158:161], v[202:205], v[52:55]
	v_mfma_f32_16x16x32_bf16 v[48:51], v[166:169], v[202:205], v[48:51]
	v_mfma_f32_16x16x32_bf16 v[44:47], v[158:161], v[210:213], v[44:47]
	v_mfma_f32_16x16x32_bf16 v[36:39], v[166:169], v[210:213], v[36:39]
	v_mfma_f32_16x16x32_bf16 v[28:31], v[158:161], v[218:221], v[28:31]
	v_mfma_f32_16x16x32_bf16 v[20:23], v[166:169], v[218:221], v[20:23]
	v_mfma_f32_16x16x32_bf16 v[60:63], v[162:165], v[198:201], v[60:63]
	v_mfma_f32_16x16x32_bf16 v[56:59], v[170:173], v[198:201], v[56:59]
	v_mfma_f32_16x16x32_bf16 v[52:55], v[162:165], v[206:209], v[52:55]
	v_mfma_f32_16x16x32_bf16 v[48:51], v[170:173], v[206:209], v[48:51]
	v_mfma_f32_16x16x32_bf16 v[44:47], v[162:165], v[214:217], v[44:47]
	v_mfma_f32_16x16x32_bf16 v[36:39], v[170:173], v[214:217], v[36:39]
	v_mfma_f32_16x16x32_bf16 v[28:31], v[162:165], v[222:225], v[28:31]
	v_mfma_f32_16x16x32_bf16 v[20:23], v[170:173], v[222:225], v[20:23]
	s_setprio 0
	s_setprio 1
	v_mfma_f32_16x16x32_bf16 v[40:43], v[174:177], v[194:197], v[40:43]
	v_mfma_f32_16x16x32_bf16 v[32:35], v[186:189], v[194:197], v[32:35]
	v_mfma_f32_16x16x32_bf16 v[24:27], v[174:177], v[202:205], v[24:27]
	v_mfma_f32_16x16x32_bf16 v[16:19], v[186:189], v[202:205], v[16:19]
	v_mfma_f32_16x16x32_bf16 v[12:15], v[174:177], v[210:213], v[12:15]
	v_mfma_f32_16x16x32_bf16 v[8:11], v[186:189], v[210:213], v[8:11]
	v_mfma_f32_16x16x32_bf16 v[4:7], v[174:177], v[218:221], v[4:7]
	v_mfma_f32_16x16x32_bf16 v[0:3], v[186:189], v[218:221], v[0:3]
	v_mfma_f32_16x16x32_bf16 v[40:43], v[178:181], v[198:201], v[40:43]
	v_mfma_f32_16x16x32_bf16 v[32:35], v[190:193], v[198:201], v[32:35]
	v_mfma_f32_16x16x32_bf16 v[24:27], v[178:181], v[206:209], v[24:27]
	v_mfma_f32_16x16x32_bf16 v[16:19], v[190:193], v[206:209], v[16:19]
	v_mfma_f32_16x16x32_bf16 v[12:15], v[178:181], v[214:217], v[12:15]
	v_mfma_f32_16x16x32_bf16 v[8:11], v[190:193], v[214:217], v[8:11]
	v_mfma_f32_16x16x32_bf16 v[4:7], v[178:181], v[222:225], v[4:7]
	v_mfma_f32_16x16x32_bf16 v[0:3], v[190:193], v[222:225], v[0:3]
	s_add_i32 s44, s44, 2
	s_add_u32 s0, s0, 0x100
	s_addc_u32 s1, s1, 0
	s_add_u32 s42, s42, 0x100
	s_addc_u32 s43, s43, 0
	s_cmp_gt_u32 s44, 5
	s_setprio 0
	s_barrier
	s_cbranch_scc0 .LBB0_470
	s_ashr_i32 s0, s24, 10
	s_ashr_i32 s1, s0, 31
	s_lshl_b64 s[0:1], s[0:1], 23
	v_lshl_add_u64 v[158:159], v[138:139], 0, s[0:1]
	s_lshl_b32 s0, s23, 8
	v_add_u32_e32 v136, s0, v148
	v_lshlrev_b64 v[160:161], 10, v[136:137]
	v_lshl_add_u64 v[160:161], v[158:159], 0, v[160:161]
	global_store_dwordx4 v[160:161], v[124:127], off
	global_store_dwordx4 v[160:161], v[120:123], off offset:16
	global_store_dwordx4 v[160:161], v[104:107], off offset:512
	global_store_dwordx4 v[160:161], v[96:99], off offset:528
	s_and_b64 vcc, exec, vcc
	s_mov_b32 s24, s35
	v_add_u32_e32 v96, s0, v152
	v_mov_b32_e32 v97, v137
	v_lshlrev_b64 v[96:97], 10, v[96:97]
	v_lshl_add_u64 v[96:97], v[158:159], 0, v[96:97]
	global_store_dwordx4 v[96:97], v[116:119], off
	global_store_dwordx4 v[96:97], v[112:115], off offset:16
	global_store_dwordx4 v[96:97], v[88:91], off offset:512
	global_store_dwordx4 v[96:97], v[80:83], off offset:528
	s_mov_b32 s23, s37
	s_nop 0
	v_add_u32_e32 v80, s0, v153
	v_mov_b32_e32 v81, v137
	v_lshlrev_b64 v[80:81], 10, v[80:81]
	v_lshl_add_u64 v[80:81], v[158:159], 0, v[80:81]
	global_store_dwordx4 v[80:81], v[108:111], off
	global_store_dwordx4 v[80:81], v[100:103], off offset:16
	global_store_dwordx4 v[80:81], v[76:79], off offset:512
	global_store_dwordx4 v[80:81], v[72:75], off offset:528
	s_nop 1
	v_add_u32_e32 v72, s0, v154
	v_mov_b32_e32 v73, v137
	v_lshlrev_b64 v[72:73], 10, v[72:73]
	v_lshl_add_u64 v[72:73], v[158:159], 0, v[72:73]
	global_store_dwordx4 v[72:73], v[92:95], off
	global_store_dwordx4 v[72:73], v[84:87], off offset:16
	global_store_dwordx4 v[72:73], v[68:71], off offset:512
	global_store_dwordx4 v[72:73], v[64:67], off offset:528
	s_nop 1
	v_add_u32_e32 v64, 0x80, v136
	v_mov_b32_e32 v65, v137
	v_lshlrev_b64 v[64:65], 10, v[64:65]
	v_lshl_add_u64 v[64:65], v[158:159], 0, v[64:65]
	global_store_dwordx4 v[64:65], v[60:63], off
	global_store_dwordx4 v[64:65], v[56:59], off offset:16
	global_store_dwordx4 v[64:65], v[40:43], off offset:512
	global_store_dwordx4 v[64:65], v[32:35], off offset:528
	s_nop 1
	v_add_u32_e32 v32, 0x90, v136
	v_mov_b32_e32 v33, v137
	v_lshlrev_b64 v[32:33], 10, v[32:33]
	v_lshl_add_u64 v[32:33], v[158:159], 0, v[32:33]
	global_store_dwordx4 v[32:33], v[52:55], off
	global_store_dwordx4 v[32:33], v[48:51], off offset:16
	global_store_dwordx4 v[32:33], v[24:27], off offset:512
	global_store_dwordx4 v[32:33], v[16:19], off offset:528
	s_nop 1
	v_add_u32_e32 v16, 0xa0, v136
	v_mov_b32_e32 v17, v137
	v_lshlrev_b64 v[16:17], 10, v[16:17]
	v_lshl_add_u64 v[16:17], v[158:159], 0, v[16:17]
	v_add_u32_e32 v136, 0xb0, v136
	global_store_dwordx4 v[16:17], v[44:47], off
	global_store_dwordx4 v[16:17], v[36:39], off offset:16
	global_store_dwordx4 v[16:17], v[12:15], off offset:512
	global_store_dwordx4 v[16:17], v[8:11], off offset:528
	s_nop 1
	v_lshlrev_b64 v[8:9], 10, v[136:137]
	v_lshl_add_u64 v[8:9], v[158:159], 0, v[8:9]
	global_store_dwordx4 v[8:9], v[28:31], off
	global_store_dwordx4 v[8:9], v[20:23], off offset:16
	global_store_dwordx4 v[8:9], v[4:7], off offset:512
	global_store_dwordx4 v[8:9], v[0:3], off offset:528
	s_cbranch_vccz .LBB0_469
	s_waitcnt vmcnt(0)
	s_cmpk_gt_u32 s14, 0xff
	s_cbranch_scc1 .LBB0_474
	s_barrier

; #define PG8_STAGE(bufoff, gbase, voff) do { _Pragma("unroll") for (int _i = 0; _i < 2; ++_i) \
;         __builtin_amdgcn_global_load_lds((const unsigned*)((const char*)(gbase) + (voff)[_i]), (PG8_LAS unsigned*)(lds + (bufoff) + ldsw + _i * 8192), 16, 0, 0); } while (0)
; #define PG8_LDA(dst, b, h) do { _Pragma("unroll") for (int m = 0; m < 4; ++m) _Pragma("unroll") for (int k = 0; k < 2; ++k) dst[m][k] = *(const PG8_LAS bf16x8*)(lds + PG8_SA(b, h) + aoff + m * 2048 + k * 1024); } while (0)
; #define PG8_LDB(dst, b, h) do { _Pragma("unroll") for (int n = 0; n < 2; ++n) _Pragma("unroll") for (int k = 0; k < 2; ++k) dst[n][k] = *(const PG8_LAS bf16x8*)(lds + PG8_SB(b, h) + boff + n * 2048 + k * 1024); } while (0)
; #define PG8_MMA(ai, bj, At, Bt) do { __builtin_amdgcn_s_setprio(1); _Pragma("unroll") for (int m = 0; m < 4; ++m) _Pragma("unroll") for (int n = 0; n < 2; ++n) _Pragma("unroll") for (int k = 0; k < 2; ++k) \
;         acc[ai][bj][m][n] = __builtin_amdgcn_mfma_f32_16x16x32_bf16(Bt[n][k], At[m][k], acc[ai][bj][m][n], 0, 0, 0); __builtin_amdgcn_s_setprio(0); } while (0)
; #define PG8_WAIT_V(n) asm volatile("s_waitcnt vmcnt(" #n ")" ::: "memory")
; #define PG8_WAIT_L(n) asm volatile("s_waitcnt lgkmcnt(" #n ")" ::: "memory")
; #define PG8_BAR __builtin_amdgcn_s_barrier()
; template <class Epi, class Sched, bool ALIGN_EPI = false, bool SP2 = false>
; __device__ __forceinline__ void gemm_phase(PG8_LAS unsigned char* lds, const Gemm g, const Sched& S, const Epi& E) {
;     ...
;             const char* a1 = cA + (size_t)(t + 1) * kstep;
;             const char* a2 = last ? nA : cA + (size_t)(t + 2) * kstep; const char* b2 = last ? nB : cB + (size_t)(t + 2) * kstep;
;             const char* a3 = a2 + kstep; const char* b3 = b2 + kstep;
;             if (last && has_next) S.a_ready(nxt);
;             if constexpr (SP2) {
;             PG8_LDB(B0, 0, 0); PG8_LDB(B1, 0, 1); PG8_SCHED; PG8_LDA(At, 0, 0); PG8_STAGE(PG8_SA(1, 1), a1 + hstepA, voffA);
;             PG8_WAIT_V(8); PG8_WAIT_L(0); PG8_BAR; PG8_MMA(0, 0, At, B0); PG8_MMA(0, 1, At, B1); PG8_BAR; PG8_SCHED;
;             PG8_LDA(At, 0, 1); PG8_STAGE(PG8_SB(0, 0), b2, voffB); PG8_STAGE(PG8_SB(0, 1), b2 + hstepB, voffB); PG8_STAGE(PG8_SA(0, 0), a2, voffA);
;             PG8_WAIT_V(8); PG8_WAIT_L(0); PG8_BAR; PG8_MMA(1, 0, At, B0); PG8_MMA(1, 1, At, B1); PG8_BAR; PG8_SCHED;
.LBB0_935:
	ds_read_b128 v[120:123], v237
	ds_read_b128 v[124:127], v237 offset:1024
	ds_read_b128 v[136:139], v237 offset:2048
	ds_read_b128 v[140:143], v237 offset:3072
	ds_read_b128 v[144:147], v238
	ds_read_b128 v[148:151], v238 offset:1024
	ds_read_b128 v[152:155], v238 offset:2048
	ds_read_b128 v[156:159], v238 offset:3072
	s_add_u32 s38, s36, 0xfffc0080
	s_addc_u32 s39, s37, -1
	s_cmp_eq_u32 s58, 12
	s_cselect_b32 s41, s9, s39
	s_cselect_b32 s40, s27, s38
	s_cselect_b32 s39, s25, s57
	s_cselect_b32 s38, s35, s56
	v_lshl_add_u64 v[214:215], s[36:37], 0, v[198:199]
	s_add_i32 m0, s44, 0xc000
	ds_read_b128 v[160:163], v239
	ds_read_b128 v[164:167], v239 offset:1024
	ds_read_b128 v[168:171], v239 offset:2048
	ds_read_b128 v[172:175], v239 offset:3072
	ds_read_b128 v[176:179], v239 offset:4096
	ds_read_b128 v[180:183], v239 offset:5120
	ds_read_b128 v[206:209], v239 offset:6144
	ds_read_b128 v[210:213], v239 offset:7168
	global_load_lds_dwordx4 v[214:215], off
	v_lshl_add_u64 v[214:215], s[36:37], 0, v[200:201]
	s_add_i32 m0, s44, 0xe000
	s_nop 0
	global_load_lds_dwordx4 v[214:215], off
	s_waitcnt vmcnt(8)
	s_waitcnt lgkmcnt(0)
	s_barrier
	s_setprio 1
	s_waitcnt lgkmcnt(0)
	v_mfma_f32_16x16x32_bf16 v[132:135], v[120:123], v[160:163], v[132:135]
	v_mfma_f32_16x16x32_bf16 v[128:131], v[136:139], v[160:163], v[128:131]
	v_mfma_f32_16x16x32_bf16 v[108:111], v[120:123], v[168:171], v[108:111]
	v_mfma_f32_16x16x32_bf16 v[104:107], v[136:139], v[168:171], v[104:107]
	v_mfma_f32_16x16x32_bf16 v[92:95], v[120:123], v[176:179], v[92:95]
	v_mfma_f32_16x16x32_bf16 v[88:91], v[136:139], v[176:179], v[88:91]
	v_mfma_f32_16x16x32_bf16 v[76:79], v[120:123], v[206:209], v[76:79]
	v_mfma_f32_16x16x32_bf16 v[72:75], v[136:139], v[206:209], v[72:75]
	v_mfma_f32_16x16x32_bf16 v[132:135], v[124:127], v[164:167], v[132:135]
	v_mfma_f32_16x16x32_bf16 v[128:131], v[140:143], v[164:167], v[128:131]
	v_mfma_f32_16x16x32_bf16 v[108:111], v[124:127], v[172:175], v[108:111]
	v_mfma_f32_16x16x32_bf16 v[104:107], v[140:143], v[172:175], v[104:107]
	v_mfma_f32_16x16x32_bf16 v[92:95], v[124:127], v[180:183], v[92:95]
	v_mfma_f32_16x16x32_bf16 v[88:91], v[140:143], v[180:183], v[88:91]
	v_mfma_f32_16x16x32_bf16 v[76:79], v[124:127], v[210:213], v[76:79]
	v_mfma_f32_16x16x32_bf16 v[72:75], v[140:143], v[210:213], v[72:75]
	s_setprio 0
	s_setprio 1
	v_mfma_f32_16x16x32_bf16 v[116:119], v[144:147], v[160:163], v[116:119]
	v_mfma_f32_16x16x32_bf16 v[112:115], v[152:155], v[160:163], v[112:115]
	v_mfma_f32_16x16x32_bf16 v[100:103], v[144:147], v[168:171], v[100:103]
	v_mfma_f32_16x16x32_bf16 v[96:99], v[152:155], v[168:171], v[96:99]
	v_mfma_f32_16x16x32_bf16 v[84:87], v[144:147], v[176:179], v[84:87]
	v_mfma_f32_16x16x32_bf16 v[80:83], v[152:155], v[176:179], v[80:83]
	v_mfma_f32_16x16x32_bf16 v[68:71], v[144:147], v[206:209], v[68:71]
	v_mfma_f32_16x16x32_bf16 v[64:67], v[152:155], v[206:209], v[64:67]
	v_mfma_f32_16x16x32_bf16 v[116:119], v[148:151], v[164:167], v[116:119]
	v_mfma_f32_16x16x32_bf16 v[112:115], v[156:159], v[164:167], v[112:115]
	v_mfma_f32_16x16x32_bf16 v[100:103], v[148:151], v[172:175], v[100:103]
	v_mfma_f32_16x16x32_bf16 v[96:99], v[156:159], v[172:175], v[96:99]
	v_mfma_f32_16x16x32_bf16 v[84:87], v[148:151], v[180:183], v[84:87]
	v_mfma_f32_16x16x32_bf16 v[80:83], v[156:159], v[180:183], v[80:83]
	v_mfma_f32_16x16x32_bf16 v[68:71], v[148:151], v[210:213], v[68:71]
	v_mfma_f32_16x16x32_bf16 v[64:67], v[156:159], v[210:213], v[64:67]
	s_setprio 0
	s_barrier
	s_add_i32 s59, s53, s43
	v_lshl_add_u64 v[214:215], s[38:39], 0, v[188:189]
	s_mov_b32 m0, s59
	ds_read_b128 v[160:163], v239 offset:16384
	ds_read_b128 v[164:167], v239 offset:17408
	ds_read_b128 v[168:171], v239 offset:18432
	ds_read_b128 v[172:175], v239 offset:19456
	ds_read_b128 v[176:179], v239 offset:20480
	ds_read_b128 v[180:183], v239 offset:21504
	ds_read_b128 v[206:209], v239 offset:22528
	ds_read_b128 v[210:213], v239 offset:23552
	global_load_lds_dwordx4 v[214:215], off
	s_add_i32 m0, s59, 0x2000
	s_add_u32 s60, s38, 0x40000
	v_lshl_add_u64 v[216:217], s[38:39], 0, v[192:193]
	s_addc_u32 s61, s39, 0
	s_add_i32 s59, s54, s43
	global_load_lds_dwordx4 v[216:217], off
	v_lshl_add_u64 v[218:219], s[60:61], 0, v[188:189]
	s_mov_b32 m0, s59
	v_lshl_add_u64 v[220:221], s[40:41], 0, v[190:191]
	global_load_lds_dwordx4 v[218:219], off
	v_lshl_add_u64 v[218:219], s[60:61], 0, v[192:193]
	s_add_i32 m0, s59, 0x2000
	s_nop 0
	global_load_lds_dwordx4 v[218:219], off
	v_lshl_add_u64 v[218:219], s[40:41], 0, v[186:187]
	s_mov_b32 m0, s44
	s_nop 0
	global_load_lds_dwordx4 v[218:219], off
	s_mov_b32 m0, s45
	s_nop 0
	global_load_lds_dwordx4 v[220:221], off
	s_waitcnt vmcnt(8)
	s_waitcnt lgkmcnt(0)
	s_barrier
; #define PG8_STAGE(bufoff, gbase, voff) do { _Pragma("unroll") for (int _i = 0; _i < 2; ++_i) \
;         __builtin_amdgcn_global_load_lds((const unsigned*)((const char*)(gbase) + (voff)[_i]), (PG8_LAS unsigned*)(lds + (bufoff) + ldsw + _i * 8192), 16, 0, 0); } while (0)
; #define PG8_LDA(dst, b, h) do { _Pragma("unroll") for (int m = 0; m < 4; ++m) _Pragma("unroll") for (int k = 0; k < 2; ++k) dst[m][k] = *(const PG8_LAS bf16x8*)(lds + PG8_SA(b, h) + aoff + m * 2048 + k * 1024); } while (0)
; #define PG8_LDB(dst, b, h) do { _Pragma("unroll") for (int n = 0; n < 2; ++n) _Pragma("unroll") for (int k = 0; k < 2; ++k) dst[n][k] = *(const PG8_LAS bf16x8*)(lds + PG8_SB(b, h) + boff + n * 2048 + k * 1024); } while (0)
; #define PG8_MMA(ai, bj, At, Bt) do { __builtin_amdgcn_s_setprio(1); _Pragma("unroll") for (int m = 0; m < 4; ++m) _Pragma("unroll") for (int n = 0; n < 2; ++n) _Pragma("unroll") for (int k = 0; k < 2; ++k) \
;         acc[ai][bj][m][n] = __builtin_amdgcn_mfma_f32_16x16x32_bf16(Bt[n][k], At[m][k], acc[ai][bj][m][n], 0, 0, 0); __builtin_amdgcn_s_setprio(0); } while (0)
; #define PG8_WAIT_V(n) asm volatile("s_waitcnt vmcnt(" #n ")" ::: "memory")
; #define PG8_WAIT_L(n) asm volatile("s_waitcnt lgkmcnt(" #n ")" ::: "memory")
; #define PG8_BAR __builtin_amdgcn_s_barrier()
; #define PG8_SCHED __builtin_amdgcn_sched_barrier(0)
; template <class Epi, class Sched, bool ALIGN_EPI = false, bool SP2 = false>
; __device__ __forceinline__ void gemm_phase(PG8_LAS unsigned char* lds, const Gemm g, const Sched& S, const Epi& E) {
;     ...
;             PG8_WAIT_V(8); PG8_WAIT_L(0); PG8_BAR; PG8_MMA(1, 0, At, B0); PG8_MMA(1, 1, At, B1); PG8_BAR; PG8_SCHED;
;             PG8_LDB(B0, 1, 0); PG8_LDB(B1, 1, 1); PG8_SCHED; PG8_LDA(At, 1, 0); PG8_STAGE(PG8_SA(0, 1), a2 + hstepA, voffA);
;             PG8_WAIT_V(8); PG8_WAIT_L(0); PG8_BAR; PG8_MMA(0, 0, At, B0); PG8_MMA(0, 1, At, B1); PG8_BAR; PG8_SCHED;
	s_setprio 1
	s_waitcnt lgkmcnt(0)
	v_mfma_f32_16x16x32_bf16 v[60:63], v[120:123], v[160:163], v[60:63]
	v_mfma_f32_16x16x32_bf16 v[56:59], v[136:139], v[160:163], v[56:59]
	v_mfma_f32_16x16x32_bf16 v[44:47], v[120:123], v[168:171], v[44:47]
	v_mfma_f32_16x16x32_bf16 v[40:43], v[136:139], v[168:171], v[40:43]
	v_mfma_f32_16x16x32_bf16 v[28:31], v[120:123], v[176:179], v[28:31]
	v_mfma_f32_16x16x32_bf16 v[24:27], v[136:139], v[176:179], v[24:27]
	v_mfma_f32_16x16x32_bf16 v[12:15], v[120:123], v[206:209], v[12:15]
	v_mfma_f32_16x16x32_bf16 v[8:11], v[136:139], v[206:209], v[8:11]
	v_mfma_f32_16x16x32_bf16 v[60:63], v[124:127], v[164:167], v[60:63]
	v_mfma_f32_16x16x32_bf16 v[56:59], v[140:143], v[164:167], v[56:59]
	v_mfma_f32_16x16x32_bf16 v[44:47], v[124:127], v[172:175], v[44:47]
	v_mfma_f32_16x16x32_bf16 v[40:43], v[140:143], v[172:175], v[40:43]
	v_mfma_f32_16x16x32_bf16 v[28:31], v[124:127], v[180:183], v[28:31]
	v_mfma_f32_16x16x32_bf16 v[24:27], v[140:143], v[180:183], v[24:27]
	v_mfma_f32_16x16x32_bf16 v[12:15], v[124:127], v[210:213], v[12:15]
	v_mfma_f32_16x16x32_bf16 v[8:11], v[140:143], v[210:213], v[8:11]
	s_setprio 0
	s_setprio 1
	v_mfma_f32_16x16x32_bf16 v[52:55], v[144:147], v[160:163], v[52:55]
	v_mfma_f32_16x16x32_bf16 v[48:51], v[152:155], v[160:163], v[48:51]
	v_mfma_f32_16x16x32_bf16 v[36:39], v[144:147], v[168:171], v[36:39]
	v_mfma_f32_16x16x32_bf16 v[32:35], v[152:155], v[168:171], v[32:35]
	v_mfma_f32_16x16x32_bf16 v[20:23], v[144:147], v[176:179], v[20:23]
	v_mfma_f32_16x16x32_bf16 v[16:19], v[152:155], v[176:179], v[16:19]
	v_mfma_f32_16x16x32_bf16 v[4:7], v[144:147], v[206:209], v[4:7]
	v_mfma_f32_16x16x32_bf16 v[0:3], v[152:155], v[206:209], v[0:3]
	v_mfma_f32_16x16x32_bf16 v[52:55], v[148:151], v[164:167], v[52:55]
	v_mfma_f32_16x16x32_bf16 v[48:51], v[156:159], v[164:167], v[48:51]
	v_mfma_f32_16x16x32_bf16 v[36:39], v[148:151], v[172:175], v[36:39]
	v_mfma_f32_16x16x32_bf16 v[32:35], v[156:159], v[172:175], v[32:35]
	v_mfma_f32_16x16x32_bf16 v[20:23], v[148:151], v[180:183], v[20:23]
	v_mfma_f32_16x16x32_bf16 v[16:19], v[156:159], v[180:183], v[16:19]
	v_mfma_f32_16x16x32_bf16 v[4:7], v[148:151], v[210:213], v[4:7]
	v_mfma_f32_16x16x32_bf16 v[0:3], v[156:159], v[210:213], v[0:3]
	s_setprio 0
	s_barrier
	s_add_i32 s59, 0, 0x18000
	s_add_i32 s60, 0, 0x1c000
	v_add_u32_e32 v140, s59, v234
	v_add_u32_e32 v156, s60, v234
	ds_read_b128 v[120:123], v140
	ds_read_b128 v[124:127], v140 offset:1024
	ds_read_b128 v[136:139], v140 offset:2048
	ds_read_b128 v[140:143], v140 offset:3072
	ds_read_b128 v[144:147], v156
	ds_read_b128 v[148:151], v156 offset:1024
	ds_read_b128 v[152:155], v156 offset:2048
	ds_read_b128 v[156:159], v156 offset:3072
	s_add_u32 s40, s40, 0x40000
	s_addc_u32 s41, s41, 0
	s_mov_b32 m0, s46
	v_lshl_add_u64 v[222:223], s[40:41], 0, v[186:187]
	ds_read_b128 v[160:163], v239 offset:32768
	ds_read_b128 v[164:167], v239 offset:33792
	ds_read_b128 v[168:171], v239 offset:34816
	ds_read_b128 v[172:175], v239 offset:35840
	ds_read_b128 v[176:179], v239 offset:36864
	ds_read_b128 v[180:183], v239 offset:37888
	ds_read_b128 v[206:209], v239 offset:38912
	ds_read_b128 v[210:213], v239 offset:39936
	global_load_lds_dwordx4 v[222:223], off
	v_lshl_add_u64 v[222:223], s[40:41], 0, v[190:191]
	s_mov_b32 m0, s47
	s_nop 0
	global_load_lds_dwordx4 v[222:223], off
	s_waitcnt vmcnt(8)
	s_waitcnt lgkmcnt(0)
	s_barrier
	s_setprio 1
	s_waitcnt lgkmcnt(0)
	v_mfma_f32_16x16x32_bf16 v[132:135], v[120:123], v[160:163], v[132:135]
	v_mfma_f32_16x16x32_bf16 v[128:131], v[136:139], v[160:163], v[128:131]
	v_mfma_f32_16x16x32_bf16 v[108:111], v[120:123], v[168:171], v[108:111]
	v_mfma_f32_16x16x32_bf16 v[104:107], v[136:139], v[168:171], v[104:107]
	v_mfma_f32_16x16x32_bf16 v[92:95], v[120:123], v[176:179], v[92:95]
	v_mfma_f32_16x16x32_bf16 v[88:91], v[136:139], v[176:179], v[88:91]
	v_mfma_f32_16x16x32_bf16 v[76:79], v[120:123], v[206:209], v[76:79]
	v_mfma_f32_16x16x32_bf16 v[72:75], v[136:139], v[206:209], v[72:75]
	v_mfma_f32_16x16x32_bf16 v[132:135], v[124:127], v[164:167], v[132:135]
	v_mfma_f32_16x16x32_bf16 v[128:131], v[140:143], v[164:167], v[128:131]
	v_mfma_f32_16x16x32_bf16 v[108:111], v[124:127], v[172:175], v[108:111]
	v_mfma_f32_16x16x32_bf16 v[104:107], v[140:143], v[172:175], v[104:107]
	v_mfma_f32_16x16x32_bf16 v[92:95], v[124:127], v[180:183], v[92:95]
	v_mfma_f32_16x16x32_bf16 v[88:91], v[140:143], v[180:183], v[88:91]
	v_mfma_f32_16x16x32_bf16 v[76:79], v[124:127], v[210:213], v[76:79]
	v_mfma_f32_16x16x32_bf16 v[72:75], v[140:143], v[210:213], v[72:75]
	s_setprio 0
	s_setprio 1
	v_mfma_f32_16x16x32_bf16 v[116:119], v[144:147], v[160:163], v[116:119]
	v_mfma_f32_16x16x32_bf16 v[112:115], v[152:155], v[160:163], v[112:115]
	v_mfma_f32_16x16x32_bf16 v[100:103], v[144:147], v[168:171], v[100:103]
	v_mfma_f32_16x16x32_bf16 v[96:99], v[152:155], v[168:171], v[96:99]
	v_mfma_f32_16x16x32_bf16 v[84:87], v[144:147], v[176:179], v[84:87]
	v_mfma_f32_16x16x32_bf16 v[80:83], v[152:155], v[176:179], v[80:83]
	v_mfma_f32_16x16x32_bf16 v[68:71], v[144:147], v[206:209], v[68:71]
	v_mfma_f32_16x16x32_bf16 v[64:67], v[152:155], v[206:209], v[64:67]
	v_mfma_f32_16x16x32_bf16 v[116:119], v[148:151], v[164:167], v[116:119]
	v_mfma_f32_16x16x32_bf16 v[112:115], v[156:159], v[164:167], v[112:115]
	v_mfma_f32_16x16x32_bf16 v[100:103], v[148:151], v[172:175], v[100:103]
	v_mfma_f32_16x16x32_bf16 v[96:99], v[156:159], v[172:175], v[96:99]
	v_mfma_f32_16x16x32_bf16 v[84:87], v[148:151], v[180:183], v[84:87]
	v_mfma_f32_16x16x32_bf16 v[80:83], v[156:159], v[180:183], v[80:83]
	v_mfma_f32_16x16x32_bf16 v[68:71], v[148:151], v[210:213], v[68:71]
	v_mfma_f32_16x16x32_bf16 v[64:67], v[156:159], v[210:213], v[64:67]
	s_setprio 0
	s_barrier
; #define PG8_STAGE(bufoff, gbase, voff) do { _Pragma("unroll") for (int _i = 0; _i < 2; ++_i) \
;         __builtin_amdgcn_global_load_lds((const unsigned*)((const char*)(gbase) + (voff)[_i]), (PG8_LAS unsigned*)(lds + (bufoff) + ldsw + _i * 8192), 16, 0, 0); } while (0)
; #define PG8_LDA(dst, b, h) do { _Pragma("unroll") for (int m = 0; m < 4; ++m) _Pragma("unroll") for (int k = 0; k < 2; ++k) dst[m][k] = *(const PG8_LAS bf16x8*)(lds + PG8_SA(b, h) + aoff + m * 2048 + k * 1024); } while (0)
; #define PG8_MMA(ai, bj, At, Bt) do { __builtin_amdgcn_s_setprio(1); _Pragma("unroll") for (int m = 0; m < 4; ++m) _Pragma("unroll") for (int n = 0; n < 2; ++n) _Pragma("unroll") for (int k = 0; k < 2; ++k) \
;         acc[ai][bj][m][n] = __builtin_amdgcn_mfma_f32_16x16x32_bf16(Bt[n][k], At[m][k], acc[ai][bj][m][n], 0, 0, 0); __builtin_amdgcn_s_setprio(0); } while (0)
; #define PG8_WAIT_V(n) asm volatile("s_waitcnt vmcnt(" #n ")" ::: "memory")
; #define PG8_WAIT_L(n) asm volatile("s_waitcnt lgkmcnt(" #n ")" ::: "memory")
; #define PG8_BAR __builtin_amdgcn_s_barrier()
; #define PG8_SCHED __builtin_amdgcn_sched_barrier(0)
; template <class Epi, class Sched, bool ALIGN_EPI = false, bool SP2 = false>
; __device__ __forceinline__ void gemm_phase(PG8_LAS unsigned char* lds, const Gemm g, const Sched& S, const Epi& E) {
;     ...
;         for (int t = 0; t < nt; t += 2) {
;     ...
;             PG8_LDA(At, 1, 1); PG8_STAGE(PG8_SB(1, 0), b3, voffB); PG8_STAGE(PG8_SB(1, 1), b3 + hstepB, voffB); PG8_STAGE(PG8_SA(1, 0), a3, voffA);
;             PG8_WAIT_V(8); PG8_WAIT_L(0); PG8_BAR; PG8_MMA(1, 0, At, B0); PG8_MMA(1, 1, At, B1); PG8_BAR; PG8_SCHED;
	s_add_i32 s40, s59, s43
	v_lshl_add_u64 v[214:215], v[214:215], 0, s[20:21]
	s_mov_b32 m0, s40
	ds_read_b128 v[160:163], v239 offset:49152
	ds_read_b128 v[164:167], v239 offset:50176
	ds_read_b128 v[168:171], v239 offset:51200
	ds_read_b128 v[172:175], v239 offset:52224
	ds_read_b128 v[176:179], v239 offset:53248
	ds_read_b128 v[180:183], v239 offset:54272
	ds_read_b128 v[206:209], v239 offset:55296
	ds_read_b128 v[210:213], v239 offset:56320
	global_load_lds_dwordx4 v[214:215], off
	s_add_i32 m0, s40, 0x2000
	s_add_u32 s38, s38, 0x40080
	v_lshl_add_u64 v[214:215], v[216:217], 0, s[20:21]
	s_addc_u32 s39, s39, 0
	s_add_i32 s40, s60, s43
	global_load_lds_dwordx4 v[214:215], off
	v_lshl_add_u64 v[214:215], s[38:39], 0, v[188:189]
	s_mov_b32 m0, s40
	s_nop 0
	global_load_lds_dwordx4 v[214:215], off
	v_lshl_add_u64 v[214:215], s[38:39], 0, v[192:193]
	s_add_i32 m0, s40, 0x2000
	s_nop 0
	global_load_lds_dwordx4 v[214:215], off
	v_lshl_add_u64 v[214:215], v[218:219], 0, s[20:21]
	s_mov_b32 m0, s48
	s_nop 0
	global_load_lds_dwordx4 v[214:215], off
	v_lshl_add_u64 v[214:215], v[220:221], 0, s[20:21]
	s_mov_b32 m0, s49
	s_nop 0
	global_load_lds_dwordx4 v[214:215], off
	s_waitcnt vmcnt(8)
	s_waitcnt lgkmcnt(0)
	s_barrier
	s_setprio 1
	s_waitcnt lgkmcnt(0)
	v_mfma_f32_16x16x32_bf16 v[60:63], v[120:123], v[160:163], v[60:63]
	v_mfma_f32_16x16x32_bf16 v[56:59], v[136:139], v[160:163], v[56:59]
	v_mfma_f32_16x16x32_bf16 v[44:47], v[120:123], v[168:171], v[44:47]
	v_mfma_f32_16x16x32_bf16 v[40:43], v[136:139], v[168:171], v[40:43]
	v_mfma_f32_16x16x32_bf16 v[28:31], v[120:123], v[176:179], v[28:31]
	v_mfma_f32_16x16x32_bf16 v[24:27], v[136:139], v[176:179], v[24:27]
	v_mfma_f32_16x16x32_bf16 v[12:15], v[120:123], v[206:209], v[12:15]
	v_mfma_f32_16x16x32_bf16 v[8:11], v[136:139], v[206:209], v[8:11]
	v_mfma_f32_16x16x32_bf16 v[60:63], v[124:127], v[164:167], v[60:63]
	v_mfma_f32_16x16x32_bf16 v[56:59], v[140:143], v[164:167], v[56:59]
	v_mfma_f32_16x16x32_bf16 v[44:47], v[124:127], v[172:175], v[44:47]
	v_mfma_f32_16x16x32_bf16 v[40:43], v[140:143], v[172:175], v[40:43]
	v_mfma_f32_16x16x32_bf16 v[28:31], v[124:127], v[180:183], v[28:31]
	v_mfma_f32_16x16x32_bf16 v[24:27], v[140:143], v[180:183], v[24:27]
	v_mfma_f32_16x16x32_bf16 v[12:15], v[124:127], v[210:213], v[12:15]
	v_mfma_f32_16x16x32_bf16 v[8:11], v[140:143], v[210:213], v[8:11]
	s_setprio 0
	s_setprio 1
	v_mfma_f32_16x16x32_bf16 v[52:55], v[144:147], v[160:163], v[52:55]
	v_mfma_f32_16x16x32_bf16 v[48:51], v[152:155], v[160:163], v[48:51]
	v_mfma_f32_16x16x32_bf16 v[36:39], v[144:147], v[168:171], v[36:39]
	v_mfma_f32_16x16x32_bf16 v[32:35], v[152:155], v[168:171], v[32:35]
	v_mfma_f32_16x16x32_bf16 v[20:23], v[144:147], v[176:179], v[20:23]
	v_mfma_f32_16x16x32_bf16 v[16:19], v[152:155], v[176:179], v[16:19]
	v_mfma_f32_16x16x32_bf16 v[4:7], v[144:147], v[206:209], v[4:7]
	v_mfma_f32_16x16x32_bf16 v[0:3], v[152:155], v[206:209], v[0:3]
	v_mfma_f32_16x16x32_bf16 v[52:55], v[148:151], v[164:167], v[52:55]
	v_mfma_f32_16x16x32_bf16 v[48:51], v[156:159], v[164:167], v[48:51]
	v_mfma_f32_16x16x32_bf16 v[36:39], v[148:151], v[172:175], v[36:39]
	v_mfma_f32_16x16x32_bf16 v[32:35], v[156:159], v[172:175], v[32:35]
	v_mfma_f32_16x16x32_bf16 v[20:23], v[148:151], v[180:183], v[20:23]
	v_mfma_f32_16x16x32_bf16 v[16:19], v[156:159], v[180:183], v[16:19]
	v_mfma_f32_16x16x32_bf16 v[4:7], v[148:151], v[210:213], v[4:7]
	v_mfma_f32_16x16x32_bf16 v[0:3], v[156:159], v[210:213], v[0:3]
	s_add_i32 s58, s58, 2
	s_add_u32 s36, s36, 0x100
	s_addc_u32 s37, s37, 0
	s_add_u32 s56, s56, 0x100
	s_addc_u32 s57, s57, 0
	s_cmp_gt_u32 s58, 13
	s_setprio 0
	s_barrier
	s_cbranch_scc0 .LBB0_935
	s_and_b64 vcc, exec, s[22:23]
	s_cbranch_vccz .LBB0_938
	s_barrier

; #define PG8_STAGE(bufoff, gbase, voff) do { _Pragma("unroll") for (int _i = 0; _i < 2; ++_i) \
;         __builtin_amdgcn_global_load_lds((const unsigned*)((const char*)(gbase) + (voff)[_i]), (PG8_LAS unsigned*)(lds + (bufoff) + ldsw + _i * 8192), 16, 0, 0); } while (0)
; #define PG8_LDA(dst, b, h) do { _Pragma("unroll") for (int m = 0; m < 4; ++m) _Pragma("unroll") for (int k = 0; k < 2; ++k) dst[m][k] = *(const PG8_LAS bf16x8*)(lds + PG8_SA(b, h) + aoff + m * 2048 + k * 1024); } while (0)
; #define PG8_LDB(dst, b, h) do { _Pragma("unroll") for (int n = 0; n < 2; ++n) _Pragma("unroll") for (int k = 0; k < 2; ++k) dst[n][k] = *(const PG8_LAS bf16x8*)(lds + PG8_SB(b, h) + boff + n * 2048 + k * 1024); } while (0)
; #define PG8_MMA(ai, bj, At, Bt) do { __builtin_amdgcn_s_setprio(1); _Pragma("unroll") for (int m = 0; m < 4; ++m) _Pragma("unroll") for (int n = 0; n < 2; ++n) _Pragma("unroll") for (int k = 0; k < 2; ++k) \
;         acc[ai][bj][m][n] = __builtin_amdgcn_mfma_f32_16x16x32_bf16(Bt[n][k], At[m][k], acc[ai][bj][m][n], 0, 0, 0); __builtin_amdgcn_s_setprio(0); } while (0)
; #define PG8_WAIT_V(n) asm volatile("s_waitcnt vmcnt(" #n ")" ::: "memory")
; #define PG8_WAIT_L(n) asm volatile("s_waitcnt lgkmcnt(" #n ")" ::: "memory")
; #define PG8_BAR __builtin_amdgcn_s_barrier()
; template <class Epi, class Sched, bool ALIGN_EPI = false, bool SP2 = false>
; __device__ __forceinline__ void gemm_phase(PG8_LAS unsigned char* lds, const Gemm g, const Sched& S, const Epi& E) {
;     ...
;             const char* a1 = cA + (size_t)(t + 1) * kstep;
;             const char* a2 = last ? nA : cA + (size_t)(t + 2) * kstep; const char* b2 = last ? nB : cB + (size_t)(t + 2) * kstep;
;             const char* a3 = a2 + kstep; const char* b3 = b2 + kstep;
;             if (last && has_next) S.a_ready(nxt);
;             if constexpr (SP2) {
;             PG8_LDB(B0, 0, 0); PG8_LDB(B1, 0, 1); PG8_SCHED; PG8_LDA(At, 0, 0); PG8_STAGE(PG8_SA(1, 1), a1 + hstepA, voffA);
;             PG8_WAIT_V(8); PG8_WAIT_L(0); PG8_BAR; PG8_MMA(0, 0, At, B0); PG8_MMA(0, 1, At, B1); PG8_BAR; PG8_SCHED;
;             PG8_LDA(At, 0, 1); PG8_STAGE(PG8_SB(0, 0), b2, voffB); PG8_STAGE(PG8_SB(0, 1), b2 + hstepB, voffB); PG8_STAGE(PG8_SA(0, 0), a2, voffA);
;             PG8_WAIT_V(8); PG8_WAIT_L(0); PG8_BAR; PG8_MMA(1, 0, At, B0); PG8_MMA(1, 1, At, B1); PG8_BAR; PG8_SCHED;
.LBB0_1007:
	ds_read_b128 v[128:131], v176
	ds_read_b128 v[132:135], v176 offset:1024
	ds_read_b128 v[136:139], v176 offset:2048
	ds_read_b128 v[140:143], v176 offset:3072
	ds_read_b128 v[162:165], v177
	ds_read_b128 v[166:169], v177 offset:1024
	ds_read_b128 v[170:173], v177 offset:2048
	ds_read_b128 v[180:183], v177 offset:3072
	s_add_u32 s36, s34, 0xfffc0080
	s_addc_u32 s37, s35, -1
	s_cmp_eq_u32 s56, 12
	s_cselect_b32 s39, s25, s37
	s_cselect_b32 s38, s52, s36
	s_cselect_b32 s37, s23, s55
	s_cselect_b32 s36, s53, s54
	v_lshl_add_u64 v[218:219], s[34:35], 0, v[154:155]
	s_add_i32 m0, s41, 0xc000
	ds_read_b128 v[186:189], v178
	ds_read_b128 v[190:193], v178 offset:1024
	ds_read_b128 v[194:197], v178 offset:2048
	ds_read_b128 v[198:201], v178 offset:3072
	ds_read_b128 v[202:205], v178 offset:4096
	ds_read_b128 v[206:209], v178 offset:5120
	ds_read_b128 v[210:213], v178 offset:6144
	ds_read_b128 v[214:217], v178 offset:7168
	global_load_lds_dwordx4 v[218:219], off
	v_lshl_add_u64 v[218:219], s[34:35], 0, v[156:157]
	s_add_i32 m0, s41, 0xe000
	s_nop 0
	global_load_lds_dwordx4 v[218:219], off
	s_waitcnt vmcnt(8)
	s_waitcnt lgkmcnt(0)
	s_barrier
	s_setprio 1
	s_waitcnt lgkmcnt(0)
	v_mfma_f32_16x16x32_bf16 v[124:127], v[128:131], v[186:189], v[124:127]
	v_mfma_f32_16x16x32_bf16 v[120:123], v[136:139], v[186:189], v[120:123]
	v_mfma_f32_16x16x32_bf16 v[108:111], v[128:131], v[194:197], v[108:111]
	v_mfma_f32_16x16x32_bf16 v[104:107], v[136:139], v[194:197], v[104:107]
	v_mfma_f32_16x16x32_bf16 v[92:95], v[128:131], v[202:205], v[92:95]
	v_mfma_f32_16x16x32_bf16 v[88:91], v[136:139], v[202:205], v[88:91]
	v_mfma_f32_16x16x32_bf16 v[76:79], v[128:131], v[210:213], v[76:79]
	v_mfma_f32_16x16x32_bf16 v[72:75], v[136:139], v[210:213], v[72:75]
	v_mfma_f32_16x16x32_bf16 v[124:127], v[132:135], v[190:193], v[124:127]
	v_mfma_f32_16x16x32_bf16 v[120:123], v[140:143], v[190:193], v[120:123]
	v_mfma_f32_16x16x32_bf16 v[108:111], v[132:135], v[198:201], v[108:111]
	v_mfma_f32_16x16x32_bf16 v[104:107], v[140:143], v[198:201], v[104:107]
	v_mfma_f32_16x16x32_bf16 v[92:95], v[132:135], v[206:209], v[92:95]
	v_mfma_f32_16x16x32_bf16 v[88:91], v[140:143], v[206:209], v[88:91]
	v_mfma_f32_16x16x32_bf16 v[76:79], v[132:135], v[214:217], v[76:79]
	v_mfma_f32_16x16x32_bf16 v[72:75], v[140:143], v[214:217], v[72:75]
	s_setprio 0
	s_setprio 1
	v_mfma_f32_16x16x32_bf16 v[116:119], v[162:165], v[186:189], v[116:119]
	v_mfma_f32_16x16x32_bf16 v[112:115], v[170:173], v[186:189], v[112:115]
	v_mfma_f32_16x16x32_bf16 v[100:103], v[162:165], v[194:197], v[100:103]
	v_mfma_f32_16x16x32_bf16 v[96:99], v[170:173], v[194:197], v[96:99]
	v_mfma_f32_16x16x32_bf16 v[84:87], v[162:165], v[202:205], v[84:87]
	v_mfma_f32_16x16x32_bf16 v[80:83], v[170:173], v[202:205], v[80:83]
	v_mfma_f32_16x16x32_bf16 v[68:71], v[162:165], v[210:213], v[68:71]
	v_mfma_f32_16x16x32_bf16 v[64:67], v[170:173], v[210:213], v[64:67]
	v_mfma_f32_16x16x32_bf16 v[116:119], v[166:169], v[190:193], v[116:119]
	v_mfma_f32_16x16x32_bf16 v[112:115], v[180:183], v[190:193], v[112:115]
	v_mfma_f32_16x16x32_bf16 v[100:103], v[166:169], v[198:201], v[100:103]
	v_mfma_f32_16x16x32_bf16 v[96:99], v[180:183], v[198:201], v[96:99]
	v_mfma_f32_16x16x32_bf16 v[84:87], v[166:169], v[206:209], v[84:87]
	v_mfma_f32_16x16x32_bf16 v[80:83], v[180:183], v[206:209], v[80:83]
	v_mfma_f32_16x16x32_bf16 v[68:71], v[166:169], v[214:217], v[68:71]
	v_mfma_f32_16x16x32_bf16 v[64:67], v[180:183], v[214:217], v[64:67]
	s_setprio 0
	s_barrier
	s_add_i32 s57, s48, s40
	v_lshl_add_u64 v[218:219], s[36:37], 0, v[146:147]
	s_mov_b32 m0, s57
	ds_read_b128 v[186:189], v178 offset:16384
	ds_read_b128 v[190:193], v178 offset:17408
	ds_read_b128 v[194:197], v178 offset:18432
	ds_read_b128 v[198:201], v178 offset:19456
	ds_read_b128 v[202:205], v178 offset:20480
	ds_read_b128 v[206:209], v178 offset:21504
	ds_read_b128 v[210:213], v178 offset:22528
	ds_read_b128 v[214:217], v178 offset:23552
	global_load_lds_dwordx4 v[218:219], off
	s_add_i32 m0, s57, 0x2000
	s_add_u32 s58, s36, 0x40000
	v_lshl_add_u64 v[220:221], s[36:37], 0, v[150:151]
	s_addc_u32 s59, s37, 0
	s_add_i32 s57, s49, s40
	global_load_lds_dwordx4 v[220:221], off
	v_lshl_add_u64 v[222:223], s[58:59], 0, v[146:147]
	s_mov_b32 m0, s57
	v_lshl_add_u64 v[224:225], s[38:39], 0, v[148:149]
	global_load_lds_dwordx4 v[222:223], off
	v_lshl_add_u64 v[222:223], s[58:59], 0, v[150:151]
	s_add_i32 m0, s57, 0x2000
	s_nop 0
	global_load_lds_dwordx4 v[222:223], off
	v_lshl_add_u64 v[222:223], s[38:39], 0, v[144:145]
	s_mov_b32 m0, s41
	s_nop 0
	global_load_lds_dwordx4 v[222:223], off
	s_mov_b32 m0, s42
	s_nop 0
	global_load_lds_dwordx4 v[224:225], off
	s_waitcnt vmcnt(8)
	s_waitcnt lgkmcnt(0)
	s_barrier
; #define PG8_STAGE(bufoff, gbase, voff) do { _Pragma("unroll") for (int _i = 0; _i < 2; ++_i) \
;         __builtin_amdgcn_global_load_lds((const unsigned*)((const char*)(gbase) + (voff)[_i]), (PG8_LAS unsigned*)(lds + (bufoff) + ldsw + _i * 8192), 16, 0, 0); } while (0)
; #define PG8_LDA(dst, b, h) do { _Pragma("unroll") for (int m = 0; m < 4; ++m) _Pragma("unroll") for (int k = 0; k < 2; ++k) dst[m][k] = *(const PG8_LAS bf16x8*)(lds + PG8_SA(b, h) + aoff + m * 2048 + k * 1024); } while (0)
; #define PG8_LDB(dst, b, h) do { _Pragma("unroll") for (int n = 0; n < 2; ++n) _Pragma("unroll") for (int k = 0; k < 2; ++k) dst[n][k] = *(const PG8_LAS bf16x8*)(lds + PG8_SB(b, h) + boff + n * 2048 + k * 1024); } while (0)
; #define PG8_MMA(ai, bj, At, Bt) do { __builtin_amdgcn_s_setprio(1); _Pragma("unroll") for (int m = 0; m < 4; ++m) _Pragma("unroll") for (int n = 0; n < 2; ++n) _Pragma("unroll") for (int k = 0; k < 2; ++k) \
;         acc[ai][bj][m][n] = __builtin_amdgcn_mfma_f32_16x16x32_bf16(Bt[n][k], At[m][k], acc[ai][bj][m][n], 0, 0, 0); __builtin_amdgcn_s_setprio(0); } while (0)
; #define PG8_WAIT_V(n) asm volatile("s_waitcnt vmcnt(" #n ")" ::: "memory")
; #define PG8_WAIT_L(n) asm volatile("s_waitcnt lgkmcnt(" #n ")" ::: "memory")
; #define PG8_BAR __builtin_amdgcn_s_barrier()
; #define PG8_SCHED __builtin_amdgcn_sched_barrier(0)
; template <class Epi, class Sched, bool ALIGN_EPI = false, bool SP2 = false>
; __device__ __forceinline__ void gemm_phase(PG8_LAS unsigned char* lds, const Gemm g, const Sched& S, const Epi& E) {
;     ...
;             PG8_WAIT_V(8); PG8_WAIT_L(0); PG8_BAR; PG8_MMA(1, 0, At, B0); PG8_MMA(1, 1, At, B1); PG8_BAR; PG8_SCHED;
;             PG8_LDB(B0, 1, 0); PG8_LDB(B1, 1, 1); PG8_SCHED; PG8_LDA(At, 1, 0); PG8_STAGE(PG8_SA(0, 1), a2 + hstepA, voffA);
;             PG8_WAIT_V(8); PG8_WAIT_L(0); PG8_BAR; PG8_MMA(0, 0, At, B0); PG8_MMA(0, 1, At, B1); PG8_BAR; PG8_SCHED;
	s_setprio 1
	s_waitcnt lgkmcnt(0)
	v_mfma_f32_16x16x32_bf16 v[60:63], v[128:131], v[186:189], v[60:63]
	v_mfma_f32_16x16x32_bf16 v[56:59], v[136:139], v[186:189], v[56:59]
	v_mfma_f32_16x16x32_bf16 v[44:47], v[128:131], v[194:197], v[44:47]
	v_mfma_f32_16x16x32_bf16 v[40:43], v[136:139], v[194:197], v[40:43]
	v_mfma_f32_16x16x32_bf16 v[28:31], v[128:131], v[202:205], v[28:31]
	v_mfma_f32_16x16x32_bf16 v[24:27], v[136:139], v[202:205], v[24:27]
	v_mfma_f32_16x16x32_bf16 v[12:15], v[128:131], v[210:213], v[12:15]
	v_mfma_f32_16x16x32_bf16 v[8:11], v[136:139], v[210:213], v[8:11]
	v_mfma_f32_16x16x32_bf16 v[60:63], v[132:135], v[190:193], v[60:63]
	v_mfma_f32_16x16x32_bf16 v[56:59], v[140:143], v[190:193], v[56:59]
	v_mfma_f32_16x16x32_bf16 v[44:47], v[132:135], v[198:201], v[44:47]
	v_mfma_f32_16x16x32_bf16 v[40:43], v[140:143], v[198:201], v[40:43]
	v_mfma_f32_16x16x32_bf16 v[28:31], v[132:135], v[206:209], v[28:31]
	v_mfma_f32_16x16x32_bf16 v[24:27], v[140:143], v[206:209], v[24:27]
	v_mfma_f32_16x16x32_bf16 v[12:15], v[132:135], v[214:217], v[12:15]
	v_mfma_f32_16x16x32_bf16 v[8:11], v[140:143], v[214:217], v[8:11]
	s_setprio 0
	s_setprio 1
	v_mfma_f32_16x16x32_bf16 v[52:55], v[162:165], v[186:189], v[52:55]
	v_mfma_f32_16x16x32_bf16 v[48:51], v[170:173], v[186:189], v[48:51]
	v_mfma_f32_16x16x32_bf16 v[36:39], v[162:165], v[194:197], v[36:39]
	v_mfma_f32_16x16x32_bf16 v[32:35], v[170:173], v[194:197], v[32:35]
	v_mfma_f32_16x16x32_bf16 v[20:23], v[162:165], v[202:205], v[20:23]
	v_mfma_f32_16x16x32_bf16 v[16:19], v[170:173], v[202:205], v[16:19]
	v_mfma_f32_16x16x32_bf16 v[4:7], v[162:165], v[210:213], v[4:7]
	v_mfma_f32_16x16x32_bf16 v[0:3], v[170:173], v[210:213], v[0:3]
	v_mfma_f32_16x16x32_bf16 v[52:55], v[166:169], v[190:193], v[52:55]
	v_mfma_f32_16x16x32_bf16 v[48:51], v[180:183], v[190:193], v[48:51]
	v_mfma_f32_16x16x32_bf16 v[36:39], v[166:169], v[198:201], v[36:39]
	v_mfma_f32_16x16x32_bf16 v[32:35], v[180:183], v[198:201], v[32:35]
	v_mfma_f32_16x16x32_bf16 v[20:23], v[166:169], v[206:209], v[20:23]
	v_mfma_f32_16x16x32_bf16 v[16:19], v[180:183], v[206:209], v[16:19]
	v_mfma_f32_16x16x32_bf16 v[4:7], v[166:169], v[214:217], v[4:7]
	v_mfma_f32_16x16x32_bf16 v[0:3], v[180:183], v[214:217], v[0:3]
	s_setprio 0
	s_barrier
	s_add_i32 s57, 0, 0x18000
	s_add_i32 s58, 0, 0x1c000
	v_add_u32_e32 v140, s57, v175
	v_add_u32_e32 v179, s58, v175
	ds_read_b128 v[128:131], v140
	ds_read_b128 v[132:135], v140 offset:1024
	ds_read_b128 v[136:139], v140 offset:2048
	ds_read_b128 v[140:143], v140 offset:3072
	ds_read_b128 v[162:165], v179
	ds_read_b128 v[166:169], v179 offset:1024
	ds_read_b128 v[170:173], v179 offset:2048
	ds_read_b128 v[180:183], v179 offset:3072
	s_add_u32 s38, s38, 0x40000
	s_addc_u32 s39, s39, 0
	s_mov_b32 m0, s43
	v_lshl_add_u64 v[226:227], s[38:39], 0, v[144:145]
	ds_read_b128 v[186:189], v178 offset:32768
	ds_read_b128 v[190:193], v178 offset:33792
	ds_read_b128 v[194:197], v178 offset:34816
	ds_read_b128 v[198:201], v178 offset:35840
	ds_read_b128 v[202:205], v178 offset:36864
	ds_read_b128 v[206:209], v178 offset:37888
	ds_read_b128 v[210:213], v178 offset:38912
	ds_read_b128 v[214:217], v178 offset:39936
	global_load_lds_dwordx4 v[226:227], off
	v_lshl_add_u64 v[226:227], s[38:39], 0, v[148:149]
	s_mov_b32 m0, s44
	s_nop 0
	global_load_lds_dwordx4 v[226:227], off
	s_waitcnt vmcnt(8)
	s_waitcnt lgkmcnt(0)
	s_barrier
	s_setprio 1
	s_waitcnt lgkmcnt(0)
	v_mfma_f32_16x16x32_bf16 v[124:127], v[128:131], v[186:189], v[124:127]
	v_mfma_f32_16x16x32_bf16 v[120:123], v[136:139], v[186:189], v[120:123]
	v_mfma_f32_16x16x32_bf16 v[108:111], v[128:131], v[194:197], v[108:111]
	v_mfma_f32_16x16x32_bf16 v[104:107], v[136:139], v[194:197], v[104:107]
	v_mfma_f32_16x16x32_bf16 v[92:95], v[128:131], v[202:205], v[92:95]
	v_mfma_f32_16x16x32_bf16 v[88:91], v[136:139], v[202:205], v[88:91]
	v_mfma_f32_16x16x32_bf16 v[76:79], v[128:131], v[210:213], v[76:79]
	v_mfma_f32_16x16x32_bf16 v[72:75], v[136:139], v[210:213], v[72:75]
	v_mfma_f32_16x16x32_bf16 v[124:127], v[132:135], v[190:193], v[124:127]
	v_mfma_f32_16x16x32_bf16 v[120:123], v[140:143], v[190:193], v[120:123]
	v_mfma_f32_16x16x32_bf16 v[108:111], v[132:135], v[198:201], v[108:111]
	v_mfma_f32_16x16x32_bf16 v[104:107], v[140:143], v[198:201], v[104:107]
	v_mfma_f32_16x16x32_bf16 v[92:95], v[132:135], v[206:209], v[92:95]
	v_mfma_f32_16x16x32_bf16 v[88:91], v[140:143], v[206:209], v[88:91]
	v_mfma_f32_16x16x32_bf16 v[76:79], v[132:135], v[214:217], v[76:79]
	v_mfma_f32_16x16x32_bf16 v[72:75], v[140:143], v[214:217], v[72:75]
	s_setprio 0
	s_setprio 1
	v_mfma_f32_16x16x32_bf16 v[116:119], v[162:165], v[186:189], v[116:119]
	v_mfma_f32_16x16x32_bf16 v[112:115], v[170:173], v[186:189], v[112:115]
	v_mfma_f32_16x16x32_bf16 v[100:103], v[162:165], v[194:197], v[100:103]
	v_mfma_f32_16x16x32_bf16 v[96:99], v[170:173], v[194:197], v[96:99]
	v_mfma_f32_16x16x32_bf16 v[84:87], v[162:165], v[202:205], v[84:87]
	v_mfma_f32_16x16x32_bf16 v[80:83], v[170:173], v[202:205], v[80:83]
	v_mfma_f32_16x16x32_bf16 v[68:71], v[162:165], v[210:213], v[68:71]
	v_mfma_f32_16x16x32_bf16 v[64:67], v[170:173], v[210:213], v[64:67]
	v_mfma_f32_16x16x32_bf16 v[116:119], v[166:169], v[190:193], v[116:119]
	v_mfma_f32_16x16x32_bf16 v[112:115], v[180:183], v[190:193], v[112:115]
	v_mfma_f32_16x16x32_bf16 v[100:103], v[166:169], v[198:201], v[100:103]
	v_mfma_f32_16x16x32_bf16 v[96:99], v[180:183], v[198:201], v[96:99]
	v_mfma_f32_16x16x32_bf16 v[84:87], v[166:169], v[206:209], v[84:87]
	v_mfma_f32_16x16x32_bf16 v[80:83], v[180:183], v[206:209], v[80:83]
	v_mfma_f32_16x16x32_bf16 v[68:71], v[166:169], v[214:217], v[68:71]
	v_mfma_f32_16x16x32_bf16 v[64:67], v[180:183], v[214:217], v[64:67]
	s_setprio 0
	s_barrier
; #define PG8_STAGE(bufoff, gbase, voff) do { _Pragma("unroll") for (int _i = 0; _i < 2; ++_i) \
;         __builtin_amdgcn_global_load_lds((const unsigned*)((const char*)(gbase) + (voff)[_i]), (PG8_LAS unsigned*)(lds + (bufoff) + ldsw + _i * 8192), 16, 0, 0); } while (0)
; #define PG8_LDA(dst, b, h) do { _Pragma("unroll") for (int m = 0; m < 4; ++m) _Pragma("unroll") for (int k = 0; k < 2; ++k) dst[m][k] = *(const PG8_LAS bf16x8*)(lds + PG8_SA(b, h) + aoff + m * 2048 + k * 1024); } while (0)
; #define PG8_MMA(ai, bj, At, Bt) do { __builtin_amdgcn_s_setprio(1); _Pragma("unroll") for (int m = 0; m < 4; ++m) _Pragma("unroll") for (int n = 0; n < 2; ++n) _Pragma("unroll") for (int k = 0; k < 2; ++k) \
;         acc[ai][bj][m][n] = __builtin_amdgcn_mfma_f32_16x16x32_bf16(Bt[n][k], At[m][k], acc[ai][bj][m][n], 0, 0, 0); __builtin_amdgcn_s_setprio(0); } while (0)
; #define PG8_WAIT_V(n) asm volatile("s_waitcnt vmcnt(" #n ")" ::: "memory")
; #define PG8_WAIT_L(n) asm volatile("s_waitcnt lgkmcnt(" #n ")" ::: "memory")
; #define PG8_BAR __builtin_amdgcn_s_barrier()
; #define PG8_SCHED __builtin_amdgcn_sched_barrier(0)
; template <class Epi, class Sched, bool ALIGN_EPI = false, bool SP2 = false>
; __device__ __forceinline__ void gemm_phase(PG8_LAS unsigned char* lds, const Gemm g, const Sched& S, const Epi& E) {
;     ...
;         for (int t = 0; t < nt; t += 2) {
;     ...
;             PG8_LDA(At, 1, 1); PG8_STAGE(PG8_SB(1, 0), b3, voffB); PG8_STAGE(PG8_SB(1, 1), b3 + hstepB, voffB); PG8_STAGE(PG8_SA(1, 0), a3, voffA);
;             PG8_WAIT_V(8); PG8_WAIT_L(0); PG8_BAR; PG8_MMA(1, 0, At, B0); PG8_MMA(1, 1, At, B1); PG8_BAR; PG8_SCHED;
	s_add_i32 s38, s57, s40
	v_lshl_add_u64 v[218:219], v[218:219], 0, s[12:13]
	s_mov_b32 m0, s38
	ds_read_b128 v[186:189], v178 offset:49152
	ds_read_b128 v[190:193], v178 offset:50176
	ds_read_b128 v[194:197], v178 offset:51200
	ds_read_b128 v[198:201], v178 offset:52224
	ds_read_b128 v[202:205], v178 offset:53248
	ds_read_b128 v[206:209], v178 offset:54272
	ds_read_b128 v[210:213], v178 offset:55296
	ds_read_b128 v[214:217], v178 offset:56320
	global_load_lds_dwordx4 v[218:219], off
	s_add_i32 m0, s38, 0x2000
	s_add_u32 s36, s36, 0x40080
	v_lshl_add_u64 v[218:219], v[220:221], 0, s[12:13]
	s_addc_u32 s37, s37, 0
	s_add_i32 s38, s58, s40
	global_load_lds_dwordx4 v[218:219], off
	v_lshl_add_u64 v[218:219], s[36:37], 0, v[146:147]
	s_mov_b32 m0, s38
	s_nop 0
	global_load_lds_dwordx4 v[218:219], off
	v_lshl_add_u64 v[218:219], s[36:37], 0, v[150:151]
	s_add_i32 m0, s38, 0x2000
	s_nop 0
	global_load_lds_dwordx4 v[218:219], off
	v_lshl_add_u64 v[218:219], v[222:223], 0, s[12:13]
	s_mov_b32 m0, s45
	s_nop 0
	global_load_lds_dwordx4 v[218:219], off
	v_lshl_add_u64 v[218:219], v[224:225], 0, s[12:13]
	s_mov_b32 m0, s46
	s_nop 0
	global_load_lds_dwordx4 v[218:219], off
	s_waitcnt vmcnt(8)
	s_waitcnt lgkmcnt(0)
	s_barrier
	s_setprio 1
	s_waitcnt lgkmcnt(0)
	v_mfma_f32_16x16x32_bf16 v[60:63], v[128:131], v[186:189], v[60:63]
	v_mfma_f32_16x16x32_bf16 v[56:59], v[136:139], v[186:189], v[56:59]
	v_mfma_f32_16x16x32_bf16 v[44:47], v[128:131], v[194:197], v[44:47]
	v_mfma_f32_16x16x32_bf16 v[40:43], v[136:139], v[194:197], v[40:43]
	v_mfma_f32_16x16x32_bf16 v[28:31], v[128:131], v[202:205], v[28:31]
	v_mfma_f32_16x16x32_bf16 v[24:27], v[136:139], v[202:205], v[24:27]
	v_mfma_f32_16x16x32_bf16 v[12:15], v[128:131], v[210:213], v[12:15]
	v_mfma_f32_16x16x32_bf16 v[8:11], v[136:139], v[210:213], v[8:11]
	v_mfma_f32_16x16x32_bf16 v[60:63], v[132:135], v[190:193], v[60:63]
	v_mfma_f32_16x16x32_bf16 v[56:59], v[140:143], v[190:193], v[56:59]
	v_mfma_f32_16x16x32_bf16 v[44:47], v[132:135], v[198:201], v[44:47]
	v_mfma_f32_16x16x32_bf16 v[40:43], v[140:143], v[198:201], v[40:43]
	v_mfma_f32_16x16x32_bf16 v[28:31], v[132:135], v[206:209], v[28:31]
	v_mfma_f32_16x16x32_bf16 v[24:27], v[140:143], v[206:209], v[24:27]
	v_mfma_f32_16x16x32_bf16 v[12:15], v[132:135], v[214:217], v[12:15]
	v_mfma_f32_16x16x32_bf16 v[8:11], v[140:143], v[214:217], v[8:11]
	s_setprio 0
	s_setprio 1
	v_mfma_f32_16x16x32_bf16 v[52:55], v[162:165], v[186:189], v[52:55]
	v_mfma_f32_16x16x32_bf16 v[48:51], v[170:173], v[186:189], v[48:51]
	v_mfma_f32_16x16x32_bf16 v[36:39], v[162:165], v[194:197], v[36:39]
	v_mfma_f32_16x16x32_bf16 v[32:35], v[170:173], v[194:197], v[32:35]
	v_mfma_f32_16x16x32_bf16 v[20:23], v[162:165], v[202:205], v[20:23]
	v_mfma_f32_16x16x32_bf16 v[16:19], v[170:173], v[202:205], v[16:19]
	v_mfma_f32_16x16x32_bf16 v[4:7], v[162:165], v[210:213], v[4:7]
	v_mfma_f32_16x16x32_bf16 v[0:3], v[170:173], v[210:213], v[0:3]
	v_mfma_f32_16x16x32_bf16 v[52:55], v[166:169], v[190:193], v[52:55]
	v_mfma_f32_16x16x32_bf16 v[48:51], v[180:183], v[190:193], v[48:51]
	v_mfma_f32_16x16x32_bf16 v[36:39], v[166:169], v[198:201], v[36:39]
	v_mfma_f32_16x16x32_bf16 v[32:35], v[180:183], v[198:201], v[32:35]
	v_mfma_f32_16x16x32_bf16 v[20:23], v[166:169], v[206:209], v[20:23]
	v_mfma_f32_16x16x32_bf16 v[16:19], v[180:183], v[206:209], v[16:19]
	v_mfma_f32_16x16x32_bf16 v[4:7], v[166:169], v[214:217], v[4:7]
	v_mfma_f32_16x16x32_bf16 v[0:3], v[180:183], v[214:217], v[0:3]
	s_add_i32 s56, s56, 2
	s_add_u32 s34, s34, 0x100
	s_addc_u32 s35, s35, 0
	s_add_u32 s54, s54, 0x100
	s_addc_u32 s55, s55, 0
	s_cmp_gt_u32 s56, 13
	s_setprio 0
	s_barrier
	s_cbranch_scc0 .LBB0_1007
	s_and_b64 vcc, exec, s[16:17]
	s_cbranch_vccz .LBB0_1010
	s_barrier

; #define PG8_STAGE(bufoff, gbase, voff) do { _Pragma("unroll") for (int _i = 0; _i < 2; ++_i) \
;         __builtin_amdgcn_global_load_lds((const unsigned*)((const char*)(gbase) + (voff)[_i]), (PG8_LAS unsigned*)(lds + (bufoff) + ldsw + _i * 8192), 16, 0, 0); } while (0)
; #define PG8_LDA(dst, b, h) do { _Pragma("unroll") for (int m = 0; m < 4; ++m) _Pragma("unroll") for (int k = 0; k < 2; ++k) dst[m][k] = *(const PG8_LAS bf16x8*)(lds + PG8_SA(b, h) + aoff + m * 2048 + k * 1024); } while (0)
; #define PG8_LDB(dst, b, h) do { _Pragma("unroll") for (int n = 0; n < 2; ++n) _Pragma("unroll") for (int k = 0; k < 2; ++k) dst[n][k] = *(const PG8_LAS bf16x8*)(lds + PG8_SB(b, h) + boff + n * 2048 + k * 1024); } while (0)
; #define PG8_MMA(ai, bj, At, Bt) do { __builtin_amdgcn_s_setprio(1); _Pragma("unroll") for (int m = 0; m < 4; ++m) _Pragma("unroll") for (int n = 0; n < 2; ++n) _Pragma("unroll") for (int k = 0; k < 2; ++k) \
;         acc[ai][bj][m][n] = __builtin_amdgcn_mfma_f32_16x16x32_bf16(Bt[n][k], At[m][k], acc[ai][bj][m][n], 0, 0, 0); __builtin_amdgcn_s_setprio(0); } while (0)
; #define PG8_WAIT_V(n) asm volatile("s_waitcnt vmcnt(" #n ")" ::: "memory")
; #define PG8_WAIT_L(n) asm volatile("s_waitcnt lgkmcnt(" #n ")" ::: "memory")
; #define PG8_BAR __builtin_amdgcn_s_barrier()
; template <class Epi, class Sched, bool ALIGN_EPI = false, bool SP2 = false>
; __device__ __forceinline__ void gemm_phase(PG8_LAS unsigned char* lds, const Gemm g, const Sched& S, const Epi& E) {
;     ...
;             const char* a1 = cA + (size_t)(t + 1) * kstep;
;             const char* a2 = last ? nA : cA + (size_t)(t + 2) * kstep; const char* b2 = last ? nB : cB + (size_t)(t + 2) * kstep;
;             const char* a3 = a2 + kstep; const char* b3 = b2 + kstep;
;             if (last && has_next) S.a_ready(nxt);
;             if constexpr (SP2) {
;             PG8_LDB(B0, 0, 0); PG8_LDB(B1, 0, 1); PG8_SCHED; PG8_LDA(At, 0, 0); PG8_STAGE(PG8_SA(1, 1), a1 + hstepA, voffA);
;             PG8_WAIT_V(8); PG8_WAIT_L(0); PG8_BAR; PG8_MMA(0, 0, At, B0); PG8_MMA(0, 1, At, B1); PG8_BAR; PG8_SCHED;
;             PG8_LDA(At, 0, 1); PG8_STAGE(PG8_SB(0, 0), b2, voffB); PG8_STAGE(PG8_SB(0, 1), b2 + hstepB, voffB); PG8_STAGE(PG8_SA(0, 0), a2, voffA);
;             PG8_WAIT_V(8); PG8_WAIT_L(0); PG8_BAR; PG8_MMA(1, 0, At, B0); PG8_MMA(1, 1, At, B1); PG8_BAR; PG8_SCHED;
.LBB0_1061:
	ds_read_b128 v[128:131], v199
	ds_read_b128 v[132:135], v199 offset:1024
	ds_read_b128 v[136:139], v199 offset:2048
	ds_read_b128 v[140:143], v199 offset:3072
	ds_read_b128 v[144:147], v200
	ds_read_b128 v[148:151], v200 offset:1024
	ds_read_b128 v[152:155], v200 offset:2048
	ds_read_b128 v[156:159], v200 offset:3072
	s_add_u32 s20, s18, 0xfff00080
	s_addc_u32 s21, s19, -1
	s_cmp_eq_u32 s45, 60
	s_cselect_b32 s23, s11, s21
	s_cselect_b32 s22, s41, s20
	s_cselect_b32 s21, s9, s44
	s_cselect_b32 s20, s42, s43
	v_lshl_add_u64 v[196:197], s[18:19], 0, v[180:181]
	s_add_i32 m0, s17, 0xc000
	ds_read_b128 v[160:163], v201
	ds_read_b128 v[164:167], v201 offset:1024
	ds_read_b128 v[188:191], v201 offset:2048
	ds_read_b128 v[192:195], v201 offset:3072
	ds_read_b128 v[202:205], v201 offset:4096
	ds_read_b128 v[206:209], v201 offset:5120
	ds_read_b128 v[210:213], v201 offset:6144
	ds_read_b128 v[214:217], v201 offset:7168
	global_load_lds_dwordx4 v[196:197], off
	v_lshl_add_u64 v[196:197], s[18:19], 0, v[182:183]
	s_add_i32 m0, s17, 0xe000
	s_nop 0
	global_load_lds_dwordx4 v[196:197], off
	s_waitcnt vmcnt(8)
	s_waitcnt lgkmcnt(0)
	s_barrier
	s_setprio 1
	s_waitcnt lgkmcnt(0)
	v_mfma_f32_16x16x32_bf16 v[124:127], v[128:131], v[160:163], v[124:127]
	v_mfma_f32_16x16x32_bf16 v[120:123], v[136:139], v[160:163], v[120:123]
	v_mfma_f32_16x16x32_bf16 v[112:115], v[128:131], v[188:191], v[112:115]
	v_mfma_f32_16x16x32_bf16 v[104:107], v[136:139], v[188:191], v[104:107]
	v_mfma_f32_16x16x32_bf16 v[96:99], v[128:131], v[202:205], v[96:99]
	v_mfma_f32_16x16x32_bf16 v[88:91], v[136:139], v[202:205], v[88:91]
	v_mfma_f32_16x16x32_bf16 v[80:83], v[128:131], v[210:213], v[80:83]
	v_mfma_f32_16x16x32_bf16 v[72:75], v[136:139], v[210:213], v[72:75]
	v_mfma_f32_16x16x32_bf16 v[124:127], v[132:135], v[164:167], v[124:127]
	v_mfma_f32_16x16x32_bf16 v[120:123], v[140:143], v[164:167], v[120:123]
	v_mfma_f32_16x16x32_bf16 v[112:115], v[132:135], v[192:195], v[112:115]
	v_mfma_f32_16x16x32_bf16 v[104:107], v[140:143], v[192:195], v[104:107]
	v_mfma_f32_16x16x32_bf16 v[96:99], v[132:135], v[206:209], v[96:99]
	v_mfma_f32_16x16x32_bf16 v[88:91], v[140:143], v[206:209], v[88:91]
	v_mfma_f32_16x16x32_bf16 v[80:83], v[132:135], v[214:217], v[80:83]
	v_mfma_f32_16x16x32_bf16 v[72:75], v[140:143], v[214:217], v[72:75]
	s_setprio 0
	s_setprio 1
	v_mfma_f32_16x16x32_bf16 v[116:119], v[144:147], v[160:163], v[116:119]
	v_mfma_f32_16x16x32_bf16 v[108:111], v[152:155], v[160:163], v[108:111]
	v_mfma_f32_16x16x32_bf16 v[100:103], v[144:147], v[188:191], v[100:103]
	v_mfma_f32_16x16x32_bf16 v[92:95], v[152:155], v[188:191], v[92:95]
	v_mfma_f32_16x16x32_bf16 v[84:87], v[144:147], v[202:205], v[84:87]
	v_mfma_f32_16x16x32_bf16 v[76:79], v[152:155], v[202:205], v[76:79]
	v_mfma_f32_16x16x32_bf16 v[68:71], v[144:147], v[210:213], v[68:71]
	v_mfma_f32_16x16x32_bf16 v[64:67], v[152:155], v[210:213], v[64:67]
	v_mfma_f32_16x16x32_bf16 v[116:119], v[148:151], v[164:167], v[116:119]
	v_mfma_f32_16x16x32_bf16 v[108:111], v[156:159], v[164:167], v[108:111]
	v_mfma_f32_16x16x32_bf16 v[100:103], v[148:151], v[192:195], v[100:103]
	v_mfma_f32_16x16x32_bf16 v[92:95], v[156:159], v[192:195], v[92:95]
	v_mfma_f32_16x16x32_bf16 v[84:87], v[148:151], v[206:209], v[84:87]
	v_mfma_f32_16x16x32_bf16 v[76:79], v[156:159], v[206:209], v[76:79]
	v_mfma_f32_16x16x32_bf16 v[68:71], v[148:151], v[214:217], v[68:71]
	v_mfma_f32_16x16x32_bf16 v[64:67], v[156:159], v[214:217], v[64:67]
	s_setprio 0
	s_barrier
	s_add_i32 s46, s38, s29
	v_lshl_add_u64 v[196:197], s[20:21], 0, v[170:171]
	s_mov_b32 m0, s46
	ds_read_b128 v[160:163], v201 offset:16384
	ds_read_b128 v[164:167], v201 offset:17408
	ds_read_b128 v[188:191], v201 offset:18432
	ds_read_b128 v[192:195], v201 offset:19456
	ds_read_b128 v[202:205], v201 offset:20480
	ds_read_b128 v[206:209], v201 offset:21504
	ds_read_b128 v[210:213], v201 offset:22528
	ds_read_b128 v[214:217], v201 offset:23552
	global_load_lds_dwordx4 v[196:197], off
	s_add_i32 m0, s46, 0x2000
	s_add_u32 s46, s20, 0x100000
	v_lshl_add_u64 v[218:219], s[20:21], 0, v[174:175]
	s_addc_u32 s47, s21, 0
	s_add_i32 s48, s39, s29
	global_load_lds_dwordx4 v[218:219], off
	v_lshl_add_u64 v[220:221], s[46:47], 0, v[170:171]
	s_mov_b32 m0, s48
	v_lshl_add_u64 v[222:223], s[22:23], 0, v[172:173]
	global_load_lds_dwordx4 v[220:221], off
	v_lshl_add_u64 v[220:221], s[46:47], 0, v[174:175]
	s_add_i32 m0, s48, 0x2000
	s_nop 0
	global_load_lds_dwordx4 v[220:221], off
	v_lshl_add_u64 v[220:221], s[22:23], 0, v[168:169]
	s_mov_b32 m0, s17
	s_nop 0
	global_load_lds_dwordx4 v[220:221], off
	s_mov_b32 m0, s30
	s_nop 0
	global_load_lds_dwordx4 v[222:223], off
	s_waitcnt vmcnt(8)
	s_waitcnt lgkmcnt(0)
	s_barrier
; #define PG8_STAGE(bufoff, gbase, voff) do { _Pragma("unroll") for (int _i = 0; _i < 2; ++_i) \
;         __builtin_amdgcn_global_load_lds((const unsigned*)((const char*)(gbase) + (voff)[_i]), (PG8_LAS unsigned*)(lds + (bufoff) + ldsw + _i * 8192), 16, 0, 0); } while (0)
; #define PG8_LDA(dst, b, h) do { _Pragma("unroll") for (int m = 0; m < 4; ++m) _Pragma("unroll") for (int k = 0; k < 2; ++k) dst[m][k] = *(const PG8_LAS bf16x8*)(lds + PG8_SA(b, h) + aoff + m * 2048 + k * 1024); } while (0)
; #define PG8_LDB(dst, b, h) do { _Pragma("unroll") for (int n = 0; n < 2; ++n) _Pragma("unroll") for (int k = 0; k < 2; ++k) dst[n][k] = *(const PG8_LAS bf16x8*)(lds + PG8_SB(b, h) + boff + n * 2048 + k * 1024); } while (0)
; #define PG8_MMA(ai, bj, At, Bt) do { __builtin_amdgcn_s_setprio(1); _Pragma("unroll") for (int m = 0; m < 4; ++m) _Pragma("unroll") for (int n = 0; n < 2; ++n) _Pragma("unroll") for (int k = 0; k < 2; ++k) \
;         acc[ai][bj][m][n] = __builtin_amdgcn_mfma_f32_16x16x32_bf16(Bt[n][k], At[m][k], acc[ai][bj][m][n], 0, 0, 0); __builtin_amdgcn_s_setprio(0); } while (0)
; #define PG8_WAIT_V(n) asm volatile("s_waitcnt vmcnt(" #n ")" ::: "memory")
; #define PG8_WAIT_L(n) asm volatile("s_waitcnt lgkmcnt(" #n ")" ::: "memory")
; #define PG8_BAR __builtin_amdgcn_s_barrier()
; #define PG8_SCHED __builtin_amdgcn_sched_barrier(0)
; template <class Epi, class Sched, bool ALIGN_EPI = false, bool SP2 = false>
; __device__ __forceinline__ void gemm_phase(PG8_LAS unsigned char* lds, const Gemm g, const Sched& S, const Epi& E) {
;     ...
;             PG8_WAIT_V(8); PG8_WAIT_L(0); PG8_BAR; PG8_MMA(1, 0, At, B0); PG8_MMA(1, 1, At, B1); PG8_BAR; PG8_SCHED;
;             PG8_LDB(B0, 1, 0); PG8_LDB(B1, 1, 1); PG8_SCHED; PG8_LDA(At, 1, 0); PG8_STAGE(PG8_SA(0, 1), a2 + hstepA, voffA);
;             PG8_WAIT_V(8); PG8_WAIT_L(0); PG8_BAR; PG8_MMA(0, 0, At, B0); PG8_MMA(0, 1, At, B1); PG8_BAR; PG8_SCHED;
	s_setprio 1
	s_waitcnt lgkmcnt(0)
	v_mfma_f32_16x16x32_bf16 v[60:63], v[128:131], v[160:163], v[60:63]
	v_mfma_f32_16x16x32_bf16 v[56:59], v[136:139], v[160:163], v[56:59]
	v_mfma_f32_16x16x32_bf16 v[48:51], v[128:131], v[188:191], v[48:51]
	v_mfma_f32_16x16x32_bf16 v[40:43], v[136:139], v[188:191], v[40:43]
	v_mfma_f32_16x16x32_bf16 v[32:35], v[128:131], v[202:205], v[32:35]
	v_mfma_f32_16x16x32_bf16 v[24:27], v[136:139], v[202:205], v[24:27]
	v_mfma_f32_16x16x32_bf16 v[16:19], v[128:131], v[210:213], v[16:19]
	v_mfma_f32_16x16x32_bf16 v[8:11], v[136:139], v[210:213], v[8:11]
	v_mfma_f32_16x16x32_bf16 v[60:63], v[132:135], v[164:167], v[60:63]
	v_mfma_f32_16x16x32_bf16 v[56:59], v[140:143], v[164:167], v[56:59]
	v_mfma_f32_16x16x32_bf16 v[48:51], v[132:135], v[192:195], v[48:51]
	v_mfma_f32_16x16x32_bf16 v[40:43], v[140:143], v[192:195], v[40:43]
	v_mfma_f32_16x16x32_bf16 v[32:35], v[132:135], v[206:209], v[32:35]
	v_mfma_f32_16x16x32_bf16 v[24:27], v[140:143], v[206:209], v[24:27]
	v_mfma_f32_16x16x32_bf16 v[16:19], v[132:135], v[214:217], v[16:19]
	v_mfma_f32_16x16x32_bf16 v[8:11], v[140:143], v[214:217], v[8:11]
	s_setprio 0
	s_setprio 1
	v_mfma_f32_16x16x32_bf16 v[52:55], v[144:147], v[160:163], v[52:55]
	v_mfma_f32_16x16x32_bf16 v[44:47], v[152:155], v[160:163], v[44:47]
	v_mfma_f32_16x16x32_bf16 v[36:39], v[144:147], v[188:191], v[36:39]
	v_mfma_f32_16x16x32_bf16 v[28:31], v[152:155], v[188:191], v[28:31]
	v_mfma_f32_16x16x32_bf16 v[20:23], v[144:147], v[202:205], v[20:23]
	v_mfma_f32_16x16x32_bf16 v[12:15], v[152:155], v[202:205], v[12:15]
	v_mfma_f32_16x16x32_bf16 v[4:7], v[144:147], v[210:213], v[4:7]
	v_mfma_f32_16x16x32_bf16 v[0:3], v[152:155], v[210:213], v[0:3]
	v_mfma_f32_16x16x32_bf16 v[52:55], v[148:151], v[164:167], v[52:55]
	v_mfma_f32_16x16x32_bf16 v[44:47], v[156:159], v[164:167], v[44:47]
	v_mfma_f32_16x16x32_bf16 v[36:39], v[148:151], v[192:195], v[36:39]
	v_mfma_f32_16x16x32_bf16 v[28:31], v[156:159], v[192:195], v[28:31]
	v_mfma_f32_16x16x32_bf16 v[20:23], v[148:151], v[206:209], v[20:23]
	v_mfma_f32_16x16x32_bf16 v[12:15], v[156:159], v[206:209], v[12:15]
	v_mfma_f32_16x16x32_bf16 v[4:7], v[148:151], v[214:217], v[4:7]
	v_mfma_f32_16x16x32_bf16 v[0:3], v[156:159], v[214:217], v[0:3]
	s_setprio 0
	s_barrier
	s_add_i32 s46, 0, 0x18000
	s_add_i32 s47, 0, 0x1c000
	v_add_u32_e32 v140, s46, v198
	v_add_u32_e32 v156, s47, v198
	ds_read_b128 v[128:131], v140
	ds_read_b128 v[132:135], v140 offset:1024
	ds_read_b128 v[136:139], v140 offset:2048
	ds_read_b128 v[140:143], v140 offset:3072
	ds_read_b128 v[144:147], v156
	ds_read_b128 v[148:151], v156 offset:1024
	ds_read_b128 v[152:155], v156 offset:2048
	ds_read_b128 v[156:159], v156 offset:3072
	s_add_u32 s22, s22, 0x100000
	s_addc_u32 s23, s23, 0
	s_mov_b32 m0, s31
	v_lshl_add_u64 v[224:225], s[22:23], 0, v[168:169]
	ds_read_b128 v[160:163], v201 offset:32768
	ds_read_b128 v[164:167], v201 offset:33792
	ds_read_b128 v[188:191], v201 offset:34816
	ds_read_b128 v[192:195], v201 offset:35840
	ds_read_b128 v[202:205], v201 offset:36864
	ds_read_b128 v[206:209], v201 offset:37888
	ds_read_b128 v[210:213], v201 offset:38912
	ds_read_b128 v[214:217], v201 offset:39936
	global_load_lds_dwordx4 v[224:225], off
	v_lshl_add_u64 v[224:225], s[22:23], 0, v[172:173]
	s_mov_b32 m0, s33
	s_nop 0
	global_load_lds_dwordx4 v[224:225], off
	s_waitcnt vmcnt(8)
	s_waitcnt lgkmcnt(0)
	s_barrier
	s_setprio 1
	s_waitcnt lgkmcnt(0)
	v_mfma_f32_16x16x32_bf16 v[124:127], v[128:131], v[160:163], v[124:127]
	v_mfma_f32_16x16x32_bf16 v[120:123], v[136:139], v[160:163], v[120:123]
	v_mfma_f32_16x16x32_bf16 v[112:115], v[128:131], v[188:191], v[112:115]
	v_mfma_f32_16x16x32_bf16 v[104:107], v[136:139], v[188:191], v[104:107]
	v_mfma_f32_16x16x32_bf16 v[96:99], v[128:131], v[202:205], v[96:99]
	v_mfma_f32_16x16x32_bf16 v[88:91], v[136:139], v[202:205], v[88:91]
	v_mfma_f32_16x16x32_bf16 v[80:83], v[128:131], v[210:213], v[80:83]
	v_mfma_f32_16x16x32_bf16 v[72:75], v[136:139], v[210:213], v[72:75]
	v_mfma_f32_16x16x32_bf16 v[124:127], v[132:135], v[164:167], v[124:127]
	v_mfma_f32_16x16x32_bf16 v[120:123], v[140:143], v[164:167], v[120:123]
	v_mfma_f32_16x16x32_bf16 v[112:115], v[132:135], v[192:195], v[112:115]
	v_mfma_f32_16x16x32_bf16 v[104:107], v[140:143], v[192:195], v[104:107]
	v_mfma_f32_16x16x32_bf16 v[96:99], v[132:135], v[206:209], v[96:99]
	v_mfma_f32_16x16x32_bf16 v[88:91], v[140:143], v[206:209], v[88:91]
	v_mfma_f32_16x16x32_bf16 v[80:83], v[132:135], v[214:217], v[80:83]
	v_mfma_f32_16x16x32_bf16 v[72:75], v[140:143], v[214:217], v[72:75]
	s_setprio 0
	s_setprio 1
	v_mfma_f32_16x16x32_bf16 v[116:119], v[144:147], v[160:163], v[116:119]
	v_mfma_f32_16x16x32_bf16 v[108:111], v[152:155], v[160:163], v[108:111]
	v_mfma_f32_16x16x32_bf16 v[100:103], v[144:147], v[188:191], v[100:103]
	v_mfma_f32_16x16x32_bf16 v[92:95], v[152:155], v[188:191], v[92:95]
	v_mfma_f32_16x16x32_bf16 v[84:87], v[144:147], v[202:205], v[84:87]
	v_mfma_f32_16x16x32_bf16 v[76:79], v[152:155], v[202:205], v[76:79]
	v_mfma_f32_16x16x32_bf16 v[68:71], v[144:147], v[210:213], v[68:71]
	v_mfma_f32_16x16x32_bf16 v[64:67], v[152:155], v[210:213], v[64:67]
	v_mfma_f32_16x16x32_bf16 v[116:119], v[148:151], v[164:167], v[116:119]
	v_mfma_f32_16x16x32_bf16 v[108:111], v[156:159], v[164:167], v[108:111]
	v_mfma_f32_16x16x32_bf16 v[100:103], v[148:151], v[192:195], v[100:103]
	v_mfma_f32_16x16x32_bf16 v[92:95], v[156:159], v[192:195], v[92:95]
	v_mfma_f32_16x16x32_bf16 v[84:87], v[148:151], v[206:209], v[84:87]
	v_mfma_f32_16x16x32_bf16 v[76:79], v[156:159], v[206:209], v[76:79]
	v_mfma_f32_16x16x32_bf16 v[68:71], v[148:151], v[214:217], v[68:71]
	v_mfma_f32_16x16x32_bf16 v[64:67], v[156:159], v[214:217], v[64:67]
	s_setprio 0
	s_barrier
; #define PG8_STAGE(bufoff, gbase, voff) do { _Pragma("unroll") for (int _i = 0; _i < 2; ++_i) \
;         __builtin_amdgcn_global_load_lds((const unsigned*)((const char*)(gbase) + (voff)[_i]), (PG8_LAS unsigned*)(lds + (bufoff) + ldsw + _i * 8192), 16, 0, 0); } while (0)
; #define PG8_LDA(dst, b, h) do { _Pragma("unroll") for (int m = 0; m < 4; ++m) _Pragma("unroll") for (int k = 0; k < 2; ++k) dst[m][k] = *(const PG8_LAS bf16x8*)(lds + PG8_SA(b, h) + aoff + m * 2048 + k * 1024); } while (0)
; #define PG8_MMA(ai, bj, At, Bt) do { __builtin_amdgcn_s_setprio(1); _Pragma("unroll") for (int m = 0; m < 4; ++m) _Pragma("unroll") for (int n = 0; n < 2; ++n) _Pragma("unroll") for (int k = 0; k < 2; ++k) \
;         acc[ai][bj][m][n] = __builtin_amdgcn_mfma_f32_16x16x32_bf16(Bt[n][k], At[m][k], acc[ai][bj][m][n], 0, 0, 0); __builtin_amdgcn_s_setprio(0); } while (0)
; #define PG8_WAIT_V(n) asm volatile("s_waitcnt vmcnt(" #n ")" ::: "memory")
; #define PG8_WAIT_L(n) asm volatile("s_waitcnt lgkmcnt(" #n ")" ::: "memory")
; #define PG8_BAR __builtin_amdgcn_s_barrier()
; #define PG8_SCHED __builtin_amdgcn_sched_barrier(0)
; template <class Epi, class Sched, bool ALIGN_EPI = false, bool SP2 = false>
; __device__ __forceinline__ void gemm_phase(PG8_LAS unsigned char* lds, const Gemm g, const Sched& S, const Epi& E) {
;     ...
;         for (int t = 0; t < nt; t += 2) {
;     ...
;             PG8_LDA(At, 1, 1); PG8_STAGE(PG8_SB(1, 0), b3, voffB); PG8_STAGE(PG8_SB(1, 1), b3 + hstepB, voffB); PG8_STAGE(PG8_SA(1, 0), a3, voffA);
;             PG8_WAIT_V(8); PG8_WAIT_L(0); PG8_BAR; PG8_MMA(1, 0, At, B0); PG8_MMA(1, 1, At, B1); PG8_BAR; PG8_SCHED;
	s_add_i32 s22, s46, s29
	v_lshl_add_u64 v[196:197], v[196:197], 0, s[4:5]
	s_mov_b32 m0, s22
	ds_read_b128 v[160:163], v201 offset:49152
	ds_read_b128 v[164:167], v201 offset:50176
	ds_read_b128 v[188:191], v201 offset:51200
	ds_read_b128 v[192:195], v201 offset:52224
	ds_read_b128 v[202:205], v201 offset:53248
	ds_read_b128 v[206:209], v201 offset:54272
	ds_read_b128 v[210:213], v201 offset:55296
	ds_read_b128 v[214:217], v201 offset:56320
	global_load_lds_dwordx4 v[196:197], off
	s_add_i32 m0, s22, 0x2000
	s_add_u32 s20, s20, 0x100080
	v_lshl_add_u64 v[196:197], v[218:219], 0, s[4:5]
	s_addc_u32 s21, s21, 0
	s_add_i32 s22, s47, s29
	global_load_lds_dwordx4 v[196:197], off
	v_lshl_add_u64 v[196:197], s[20:21], 0, v[170:171]
	s_mov_b32 m0, s22
	s_nop 0
	global_load_lds_dwordx4 v[196:197], off
	v_lshl_add_u64 v[196:197], s[20:21], 0, v[174:175]
	s_add_i32 m0, s22, 0x2000
	s_nop 0
	global_load_lds_dwordx4 v[196:197], off
	v_lshl_add_u64 v[196:197], v[220:221], 0, s[4:5]
	s_mov_b32 m0, s35
	s_nop 0
	global_load_lds_dwordx4 v[196:197], off
	v_lshl_add_u64 v[196:197], v[222:223], 0, s[4:5]
	s_mov_b32 m0, s36
	s_nop 0
	global_load_lds_dwordx4 v[196:197], off
	s_waitcnt vmcnt(8)
	s_waitcnt lgkmcnt(0)
	s_barrier
	s_setprio 1
	s_waitcnt lgkmcnt(0)
	v_mfma_f32_16x16x32_bf16 v[60:63], v[128:131], v[160:163], v[60:63]
	v_mfma_f32_16x16x32_bf16 v[56:59], v[136:139], v[160:163], v[56:59]
	v_mfma_f32_16x16x32_bf16 v[48:51], v[128:131], v[188:191], v[48:51]
	v_mfma_f32_16x16x32_bf16 v[40:43], v[136:139], v[188:191], v[40:43]
	v_mfma_f32_16x16x32_bf16 v[32:35], v[128:131], v[202:205], v[32:35]
	v_mfma_f32_16x16x32_bf16 v[24:27], v[136:139], v[202:205], v[24:27]
	v_mfma_f32_16x16x32_bf16 v[16:19], v[128:131], v[210:213], v[16:19]
	v_mfma_f32_16x16x32_bf16 v[8:11], v[136:139], v[210:213], v[8:11]
	v_mfma_f32_16x16x32_bf16 v[60:63], v[132:135], v[164:167], v[60:63]
	v_mfma_f32_16x16x32_bf16 v[56:59], v[140:143], v[164:167], v[56:59]
	v_mfma_f32_16x16x32_bf16 v[48:51], v[132:135], v[192:195], v[48:51]
	v_mfma_f32_16x16x32_bf16 v[40:43], v[140:143], v[192:195], v[40:43]
	v_mfma_f32_16x16x32_bf16 v[32:35], v[132:135], v[206:209], v[32:35]
	v_mfma_f32_16x16x32_bf16 v[24:27], v[140:143], v[206:209], v[24:27]
	v_mfma_f32_16x16x32_bf16 v[16:19], v[132:135], v[214:217], v[16:19]
	v_mfma_f32_16x16x32_bf16 v[8:11], v[140:143], v[214:217], v[8:11]
	s_setprio 0
	s_setprio 1
	v_mfma_f32_16x16x32_bf16 v[52:55], v[144:147], v[160:163], v[52:55]
	v_mfma_f32_16x16x32_bf16 v[44:47], v[152:155], v[160:163], v[44:47]
	v_mfma_f32_16x16x32_bf16 v[36:39], v[144:147], v[188:191], v[36:39]
	v_mfma_f32_16x16x32_bf16 v[28:31], v[152:155], v[188:191], v[28:31]
	v_mfma_f32_16x16x32_bf16 v[20:23], v[144:147], v[202:205], v[20:23]
	v_mfma_f32_16x16x32_bf16 v[12:15], v[152:155], v[202:205], v[12:15]
	v_mfma_f32_16x16x32_bf16 v[4:7], v[144:147], v[210:213], v[4:7]
	v_mfma_f32_16x16x32_bf16 v[0:3], v[152:155], v[210:213], v[0:3]
	v_mfma_f32_16x16x32_bf16 v[52:55], v[148:151], v[164:167], v[52:55]
	v_mfma_f32_16x16x32_bf16 v[44:47], v[156:159], v[164:167], v[44:47]
	v_mfma_f32_16x16x32_bf16 v[36:39], v[148:151], v[192:195], v[36:39]
	v_mfma_f32_16x16x32_bf16 v[28:31], v[156:159], v[192:195], v[28:31]
	v_mfma_f32_16x16x32_bf16 v[20:23], v[148:151], v[206:209], v[20:23]
	v_mfma_f32_16x16x32_bf16 v[12:15], v[156:159], v[206:209], v[12:15]
	v_mfma_f32_16x16x32_bf16 v[4:7], v[148:151], v[214:217], v[4:7]
	v_mfma_f32_16x16x32_bf16 v[0:3], v[156:159], v[214:217], v[0:3]
	s_add_i32 s45, s45, 2
	s_add_u32 s18, s18, 0x100
	s_addc_u32 s19, s19, 0
	s_add_u32 s43, s43, 0x100
	s_addc_u32 s44, s44, 0
	s_cmp_gt_u32 s45, 61
	s_setprio 0
	s_barrier
	s_cbranch_scc0 .LBB0_1061
	s_and_b64 vcc, exec, s[6:7]
	s_cbranch_vccz .LBB0_1064
	s_barrier
